# G3 PLE-gate GEMM epilogue rewritten by hand: T/XB loads issued 7 steps ahead (was load-wait-compute per step), saddr addressing, no per-row exec branches
# speedup vs baseline: 1.0023x; 1.0023x over previous
; __device__ __forceinline__ unsigned pk2(float lo, float hi) { return pg8::cvt_pk_bf16(lo, hi); }
; __device__ __forceinline__ float bflo(unsigned u) { return __uint_as_float(u << 16); }
; __device__ __forceinline__ float bfhi(unsigned u) { return __uint_as_float(u & 0xffff0000u); }
; __device__ __forceinline__ f32x2 sigm2(f32x2 v) { const f32x2 a = v * -1.4426950408889634f; f32x2 e; e.x = __builtin_amdgcn_exp2f(a.x); e.y = __builtin_amdgcn_exp2f(a.y); const f32x2 d = e + 1.0f; f32x2 r; r.x = __builtin_amdgcn_rcpf(d.x); r.y = __builtin_amdgcn_rcpf(d.y); return r; }
;     __device__ __forceinline__ void operator()(const pg8::f32x4 (&acc)[2][2][4][2], const Unit& u, int wr, int wc, int fr_, int fq_) const {
;         const int lane_ = otid() & 63, fr = lane_ & 15, fq = lane_ >> 4; (void)fr_; (void)fq_;
;         const int row0 = u.pm * BM + wr * 64 + fr, col0 = u.pn * BM + wc * 32 + 8 * fq;
; #pragma unroll
;         for (int ai = 0; ai < 2; ++ai)
; #pragma unroll
;             for (int m = 0; m < 4; ++m) { const int row = row0 + ai * HALF + m * 16; if (row >= MV) continue;
; #pragma unroll
;                 for (int bj = 0; bj < 2; ++bj) { const size_t off = (size_t)row * DM + col0 + bj * HALF;
;                     const u32x4 t = *(const u32x4*)(T + off); const u32x4 xb = *(const u32x4*)(XB + off);
;                     pg8::f32x4 x0 = {bflo(xb.x), bfhi(xb.x), bflo(xb.y), bfhi(xb.y)}, x1 = {bflo(xb.z), bfhi(xb.z), bflo(xb.w), bfhi(xb.w)};
;                     const pg8::f32x4 a0 = acc[ai][bj][m][0], a1 = acc[ai][bj][m][1];
;                     { const f32x2 s0 = sigm2((f32x2){a0[0], a0[1]}), s1 = sigm2((f32x2){a0[2], a0[3]}), s2 = sigm2((f32x2){a1[0], a1[1]}), s3 = sigm2((f32x2){a1[2], a1[3]});
;                       x0[0] += s0.x * bflo(t.x); x0[1] += s0.y * bfhi(t.x); x0[2] += s1.x * bflo(t.y); x0[3] += s1.y * bfhi(t.y);
;                       x1[0] += s2.x * bflo(t.z); x1[1] += s2.y * bfhi(t.z); x1[2] += s3.x * bflo(t.w); x1[3] += s3.y * bfhi(t.w); }
;                     if (f32out) { *(pg8::f32x4*)(Xo + off) = x0; *(pg8::f32x4*)(Xo + off + 4) = x1; }
;                     else { u32x4 w; w.x = pk2(x0[0], x0[1]); w.y = pk2(x0[2], x0[3]); w.z = pk2(x1[0], x1[1]); w.w = pk2(x1[2], x1[3]); *(u32x4*)((bf16_t*)Xo + off) = w; } } }
.LBB0_1720:
	s_getreg_b32 s19, hwreg(HW_REG_HW_ID, 0, 6)
	s_and_b32 s19, s19, 63
	s_lshl_b32 s19, s19, 2
	s_add_i32 s19, s19, 0
	s_add_i32 s19, s19, 0x23e00
	v_mov_b32_e32 v140, s19
	ds_read_b32 v140, v140
	v_mbcnt_lo_u32_b32 v141, -1, 0
	s_lshl_b32 s19, s60, 8
	v_mbcnt_hi_u32_b32 v141, -1, v141
	s_waitcnt lgkmcnt(0)
	v_lshrrev_b32_e32 v140, 1, v141
	v_and_or_b32 v140, v140, 24, s19
	v_and_or_b32 v141, v141, 15, s54
	v_or_b32_e32 v140, s55, v140
	v_lshl_add_u32 v142, s59, 8, v141
	v_lshlrev_b32_e32 v202, 1, v140
	v_lshl_add_u32 v202, v142, 11, v202
	v_lshlrev_b32_e32 v206, 1, v202
	s_and_b64 vcc, exec, s[14:15]
	s_cbranch_vccz .Lg3epi_f32
	global_load_dwordx4 v[140:143], v202, s[6:7]
	global_load_dwordx4 v[144:147], v202, s[10:11]
	global_load_dwordx4 v[152:155], v202, s[6:7] offset:256
	global_load_dwordx4 v[156:159], v202, s[10:11] offset:256
	v_add_u32_e32 v203, 0x8000, v202
	global_load_dwordx4 v[160:163], v203, s[6:7]
	global_load_dwordx4 v[164:167], v203, s[10:11]
	v_add_u32_e32 v203, 0x8000, v202
	global_load_dwordx4 v[168:171], v203, s[6:7] offset:256
	global_load_dwordx4 v[172:175], v203, s[10:11] offset:256
	v_add_u32_e32 v203, 0x10000, v202
	global_load_dwordx4 v[176:179], v203, s[6:7]
	global_load_dwordx4 v[180:183], v203, s[10:11]
	v_add_u32_e32 v203, 0x10000, v202
	global_load_dwordx4 v[184:187], v203, s[6:7] offset:256
	global_load_dwordx4 v[188:191], v203, s[10:11] offset:256
	v_add_u32_e32 v203, 0x18000, v202
	global_load_dwordx4 v[192:195], v203, s[6:7]
	global_load_dwordx4 v[196:199], v203, s[10:11]
	v_mul_f32_e32 v126, s80, v126
	v_mul_f32_e32 v127, s80, v127
	v_mul_f32_e32 v128, s80, v128
	v_mul_f32_e32 v129, s80, v129
	v_mul_f32_e32 v122, s80, v122
	v_mul_f32_e32 v123, s80, v123
	v_mul_f32_e32 v124, s80, v124
	v_mul_f32_e32 v125, s80, v125
	v_exp_f32_e32 v126, v126
	v_exp_f32_e32 v127, v127
	v_exp_f32_e32 v128, v128
	v_exp_f32_e32 v129, v129
	v_exp_f32_e32 v122, v122
	v_exp_f32_e32 v123, v123
	v_exp_f32_e32 v124, v124
	v_exp_f32_e32 v125, v125
	v_add_f32_e32 v126, 1.0, v126
	v_add_f32_e32 v127, 1.0, v127
	v_add_f32_e32 v128, 1.0, v128
	v_add_f32_e32 v129, 1.0, v129
	v_add_f32_e32 v122, 1.0, v122
	v_add_f32_e32 v123, 1.0, v123
	v_add_f32_e32 v124, 1.0, v124
	v_add_f32_e32 v125, 1.0, v125
	v_rcp_f32_e32 v126, v126
	v_rcp_f32_e32 v127, v127
	v_rcp_f32_e32 v128, v128
	v_rcp_f32_e32 v129, v129
	v_rcp_f32_e32 v122, v122
	v_rcp_f32_e32 v123, v123
	v_rcp_f32_e32 v124, v124
	v_rcp_f32_e32 v125, v125
	s_waitcnt vmcnt(12)
	v_lshlrev_b32_e32 v204, 16, v140
	v_lshlrev_b32_e32 v205, 16, v144
	v_and_b32_e32 v140, 0xffff0000, v140
	v_and_b32_e32 v144, 0xffff0000, v144
	v_fma_f32 v126, v126, v204, v205
	v_fma_f32 v127, v127, v140, v144
	v_lshlrev_b32_e32 v204, 16, v141
	v_lshlrev_b32_e32 v205, 16, v145
	v_and_b32_e32 v141, 0xffff0000, v141
	v_and_b32_e32 v145, 0xffff0000, v145
	v_fma_f32 v128, v128, v204, v205
	v_fma_f32 v129, v129, v141, v145
	v_lshlrev_b32_e32 v204, 16, v142
	v_lshlrev_b32_e32 v205, 16, v146
	v_and_b32_e32 v142, 0xffff0000, v142
	v_and_b32_e32 v146, 0xffff0000, v146
	v_fma_f32 v122, v122, v204, v205
	v_fma_f32 v123, v123, v142, v146
	v_lshlrev_b32_e32 v204, 16, v143
	v_lshlrev_b32_e32 v205, 16, v147
	v_and_b32_e32 v143, 0xffff0000, v143
	v_and_b32_e32 v147, 0xffff0000, v147
	v_fma_f32 v124, v124, v204, v205
	v_fma_f32 v125, v125, v143, v147
	v_cvt_pk_bf16_f32 v140, v126, v127
	v_cvt_pk_bf16_f32 v141, v128, v129
	v_cvt_pk_bf16_f32 v142, v122, v123
	v_cvt_pk_bf16_f32 v143, v124, v125
	global_store_dwordx4 v202, v[140:143], s[4:5]
	v_add_u32_e32 v203, 0x18000, v202
	global_load_dwordx4 v[140:143], v203, s[6:7] offset:256
	global_load_dwordx4 v[144:147], v203, s[10:11] offset:256
	v_mul_f32_e32 v118, s80, v118
	v_mul_f32_e32 v119, s80, v119
	v_mul_f32_e32 v120, s80, v120
	v_mul_f32_e32 v121, s80, v121
	v_mul_f32_e32 v114, s80, v114
	v_mul_f32_e32 v115, s80, v115
	v_mul_f32_e32 v116, s80, v116
	v_mul_f32_e32 v117, s80, v117
	v_exp_f32_e32 v118, v118
	v_exp_f32_e32 v119, v119
	v_exp_f32_e32 v120, v120
	v_exp_f32_e32 v121, v121
	v_exp_f32_e32 v114, v114
	v_exp_f32_e32 v115, v115
	v_exp_f32_e32 v116, v116
	v_exp_f32_e32 v117, v117
	v_add_f32_e32 v118, 1.0, v118
	v_add_f32_e32 v119, 1.0, v119
	v_add_f32_e32 v120, 1.0, v120
	v_add_f32_e32 v121, 1.0, v121
	v_add_f32_e32 v114, 1.0, v114
	v_add_f32_e32 v115, 1.0, v115
	v_add_f32_e32 v116, 1.0, v116
	v_add_f32_e32 v117, 1.0, v117
	v_rcp_f32_e32 v118, v118
	v_rcp_f32_e32 v119, v119
	v_rcp_f32_e32 v120, v120
	v_rcp_f32_e32 v121, v121
	v_rcp_f32_e32 v114, v114
	v_rcp_f32_e32 v115, v115
	v_rcp_f32_e32 v116, v116
	v_rcp_f32_e32 v117, v117
	s_waitcnt vmcnt(13)
; __device__ __forceinline__ unsigned pk2(float lo, float hi) { return pg8::cvt_pk_bf16(lo, hi); }
; __device__ __forceinline__ float bflo(unsigned u) { return __uint_as_float(u << 16); }
; __device__ __forceinline__ float bfhi(unsigned u) { return __uint_as_float(u & 0xffff0000u); }
; __device__ __forceinline__ f32x2 sigm2(f32x2 v) { const f32x2 a = v * -1.4426950408889634f; f32x2 e; e.x = __builtin_amdgcn_exp2f(a.x); e.y = __builtin_amdgcn_exp2f(a.y); const f32x2 d = e + 1.0f; f32x2 r; r.x = __builtin_amdgcn_rcpf(d.x); r.y = __builtin_amdgcn_rcpf(d.y); return r; }
;     __device__ __forceinline__ void operator()(const pg8::f32x4 (&acc)[2][2][4][2], const Unit& u, int wr, int wc, int fr_, int fq_) const {
;     ...
;                 for (int bj = 0; bj < 2; ++bj) { const size_t off = (size_t)row * DM + col0 + bj * HALF;
;                     const u32x4 t = *(const u32x4*)(T + off); const u32x4 xb = *(const u32x4*)(XB + off);
;                     pg8::f32x4 x0 = {bflo(xb.x), bfhi(xb.x), bflo(xb.y), bfhi(xb.y)}, x1 = {bflo(xb.z), bfhi(xb.z), bflo(xb.w), bfhi(xb.w)};
;                     const pg8::f32x4 a0 = acc[ai][bj][m][0], a1 = acc[ai][bj][m][1];
;                     { const f32x2 s0 = sigm2((f32x2){a0[0], a0[1]}), s1 = sigm2((f32x2){a0[2], a0[3]}), s2 = sigm2((f32x2){a1[0], a1[1]}), s3 = sigm2((f32x2){a1[2], a1[3]});
;                       x0[0] += s0.x * bflo(t.x); x0[1] += s0.y * bfhi(t.x); x0[2] += s1.x * bflo(t.y); x0[3] += s1.y * bfhi(t.y);
;                       x1[0] += s2.x * bflo(t.z); x1[1] += s2.y * bfhi(t.z); x1[2] += s3.x * bflo(t.w); x1[3] += s3.y * bfhi(t.w); }
;                     if (f32out) { *(pg8::f32x4*)(Xo + off) = x0; *(pg8::f32x4*)(Xo + off + 4) = x1; }
;                     else { u32x4 w; w.x = pk2(x0[0], x0[1]); w.y = pk2(x0[2], x0[3]); w.z = pk2(x1[0], x1[1]); w.w = pk2(x1[2], x1[3]); *(u32x4*)((bf16_t*)Xo + off) = w; } } }
	v_lshlrev_b32_e32 v204, 16, v152
	v_lshlrev_b32_e32 v205, 16, v156
	v_and_b32_e32 v152, 0xffff0000, v152
	v_and_b32_e32 v156, 0xffff0000, v156
	v_fma_f32 v118, v118, v204, v205
	v_fma_f32 v119, v119, v152, v156
	v_lshlrev_b32_e32 v204, 16, v153
	v_lshlrev_b32_e32 v205, 16, v157
	v_and_b32_e32 v153, 0xffff0000, v153
	v_and_b32_e32 v157, 0xffff0000, v157
	v_fma_f32 v120, v120, v204, v205
	v_fma_f32 v121, v121, v153, v157
	v_lshlrev_b32_e32 v204, 16, v154
	v_lshlrev_b32_e32 v205, 16, v158
	v_and_b32_e32 v154, 0xffff0000, v154
	v_and_b32_e32 v158, 0xffff0000, v158
	v_fma_f32 v114, v114, v204, v205
	v_fma_f32 v115, v115, v154, v158
	v_lshlrev_b32_e32 v204, 16, v155
	v_lshlrev_b32_e32 v205, 16, v159
	v_and_b32_e32 v155, 0xffff0000, v155
	v_and_b32_e32 v159, 0xffff0000, v159
	v_fma_f32 v116, v116, v204, v205
	v_fma_f32 v117, v117, v155, v159
	v_cvt_pk_bf16_f32 v152, v118, v119
	v_cvt_pk_bf16_f32 v153, v120, v121
	v_cvt_pk_bf16_f32 v154, v114, v115
	v_cvt_pk_bf16_f32 v155, v116, v117
	global_store_dwordx4 v202, v[152:155], s[4:5] offset:256
	v_add_u32_e32 v203, 0x40000, v202
	global_load_dwordx4 v[152:155], v203, s[6:7]
	global_load_dwordx4 v[156:159], v203, s[10:11]
	v_mul_f32_e32 v110, s80, v110
	v_mul_f32_e32 v111, s80, v111
	v_mul_f32_e32 v112, s80, v112
	v_mul_f32_e32 v113, s80, v113
	v_mul_f32_e32 v106, s80, v106
	v_mul_f32_e32 v107, s80, v107
	v_mul_f32_e32 v108, s80, v108
	v_mul_f32_e32 v109, s80, v109
	v_exp_f32_e32 v110, v110
	v_exp_f32_e32 v111, v111
	v_exp_f32_e32 v112, v112
	v_exp_f32_e32 v113, v113
	v_exp_f32_e32 v106, v106
	v_exp_f32_e32 v107, v107
	v_exp_f32_e32 v108, v108
	v_exp_f32_e32 v109, v109
	v_add_f32_e32 v110, 1.0, v110
	v_add_f32_e32 v111, 1.0, v111
	v_add_f32_e32 v112, 1.0, v112
	v_add_f32_e32 v113, 1.0, v113
	v_add_f32_e32 v106, 1.0, v106
	v_add_f32_e32 v107, 1.0, v107
	v_add_f32_e32 v108, 1.0, v108
	v_add_f32_e32 v109, 1.0, v109
	v_rcp_f32_e32 v110, v110
	v_rcp_f32_e32 v111, v111
	v_rcp_f32_e32 v112, v112
	v_rcp_f32_e32 v113, v113
	v_rcp_f32_e32 v106, v106
	v_rcp_f32_e32 v107, v107
	v_rcp_f32_e32 v108, v108
	v_rcp_f32_e32 v109, v109
	s_waitcnt vmcnt(14)
	v_lshlrev_b32_e32 v204, 16, v160
	v_lshlrev_b32_e32 v205, 16, v164
	v_and_b32_e32 v160, 0xffff0000, v160
	v_and_b32_e32 v164, 0xffff0000, v164
	v_fma_f32 v110, v110, v204, v205
	v_fma_f32 v111, v111, v160, v164
	v_lshlrev_b32_e32 v204, 16, v161
	v_lshlrev_b32_e32 v205, 16, v165
	v_and_b32_e32 v161, 0xffff0000, v161
	v_and_b32_e32 v165, 0xffff0000, v165
	v_fma_f32 v112, v112, v204, v205
	v_fma_f32 v113, v113, v161, v165
	v_lshlrev_b32_e32 v204, 16, v162
	v_lshlrev_b32_e32 v205, 16, v166
	v_and_b32_e32 v162, 0xffff0000, v162
	v_and_b32_e32 v166, 0xffff0000, v166
	v_fma_f32 v106, v106, v204, v205
	v_fma_f32 v107, v107, v162, v166
	v_lshlrev_b32_e32 v204, 16, v163
	v_lshlrev_b32_e32 v205, 16, v167
	v_and_b32_e32 v163, 0xffff0000, v163
	v_and_b32_e32 v167, 0xffff0000, v167
	v_fma_f32 v108, v108, v204, v205
	v_fma_f32 v109, v109, v163, v167
	v_cvt_pk_bf16_f32 v160, v110, v111
	v_cvt_pk_bf16_f32 v161, v112, v113
	v_cvt_pk_bf16_f32 v162, v106, v107
	v_cvt_pk_bf16_f32 v163, v108, v109
	v_add_u32_e32 v207, 0x8000, v202
	global_store_dwordx4 v207, v[160:163], s[4:5]
	v_add_u32_e32 v203, 0x40000, v202
	global_load_dwordx4 v[160:163], v203, s[6:7] offset:256
	global_load_dwordx4 v[164:167], v203, s[10:11] offset:256
	v_mul_f32_e32 v102, s80, v102
	v_mul_f32_e32 v103, s80, v103
	v_mul_f32_e32 v104, s80, v104
	v_mul_f32_e32 v105, s80, v105
	v_mul_f32_e32 v98, s80, v98
	v_mul_f32_e32 v99, s80, v99
	v_mul_f32_e32 v100, s80, v100
	v_mul_f32_e32 v101, s80, v101
	v_exp_f32_e32 v102, v102
	v_exp_f32_e32 v103, v103
	v_exp_f32_e32 v104, v104
	v_exp_f32_e32 v105, v105
	v_exp_f32_e32 v98, v98
	v_exp_f32_e32 v99, v99
	v_exp_f32_e32 v100, v100
	v_exp_f32_e32 v101, v101
	v_add_f32_e32 v102, 1.0, v102
	v_add_f32_e32 v103, 1.0, v103
	v_add_f32_e32 v104, 1.0, v104
	v_add_f32_e32 v105, 1.0, v105
	v_add_f32_e32 v98, 1.0, v98
	v_add_f32_e32 v99, 1.0, v99
	v_add_f32_e32 v100, 1.0, v100
	v_add_f32_e32 v101, 1.0, v101
	v_rcp_f32_e32 v102, v102
	v_rcp_f32_e32 v103, v103
	v_rcp_f32_e32 v104, v104
	v_rcp_f32_e32 v105, v105
	v_rcp_f32_e32 v98, v98
	v_rcp_f32_e32 v99, v99
	v_rcp_f32_e32 v100, v100
	v_rcp_f32_e32 v101, v101
	s_waitcnt vmcnt(15)
	v_lshlrev_b32_e32 v204, 16, v168
	v_lshlrev_b32_e32 v205, 16, v172
	v_and_b32_e32 v168, 0xffff0000, v168
	v_and_b32_e32 v172, 0xffff0000, v172
	v_fma_f32 v102, v102, v204, v205
	v_fma_f32 v103, v103, v168, v172
	v_lshlrev_b32_e32 v204, 16, v169
	v_lshlrev_b32_e32 v205, 16, v173
	v_and_b32_e32 v169, 0xffff0000, v169
	v_and_b32_e32 v173, 0xffff0000, v173
	v_fma_f32 v104, v104, v204, v205
	v_fma_f32 v105, v105, v169, v173
	v_lshlrev_b32_e32 v204, 16, v170
	v_lshlrev_b32_e32 v205, 16, v174
	v_and_b32_e32 v170, 0xffff0000, v170
	v_and_b32_e32 v174, 0xffff0000, v174
	v_fma_f32 v98, v98, v204, v205
	v_fma_f32 v99, v99, v170, v174
	v_lshlrev_b32_e32 v204, 16, v171
	v_lshlrev_b32_e32 v205, 16, v175
	v_and_b32_e32 v171, 0xffff0000, v171
	v_and_b32_e32 v175, 0xffff0000, v175
	v_fma_f32 v100, v100, v204, v205
	v_fma_f32 v101, v101, v171, v175
	v_cvt_pk_bf16_f32 v168, v102, v103
	v_cvt_pk_bf16_f32 v169, v104, v105
	v_cvt_pk_bf16_f32 v170, v98, v99
	v_cvt_pk_bf16_f32 v171, v100, v101
	v_add_u32_e32 v207, 0x8000, v202
	global_store_dwordx4 v207, v[168:171], s[4:5] offset:256
	v_add_u32_e32 v203, 0x48000, v202
	global_load_dwordx4 v[168:171], v203, s[6:7]
	global_load_dwordx4 v[172:175], v203, s[10:11]
	v_mul_f32_e32 v94, s80, v94
	v_mul_f32_e32 v95, s80, v95
	v_mul_f32_e32 v96, s80, v96
	v_mul_f32_e32 v97, s80, v97
	v_mul_f32_e32 v90, s80, v90
	v_mul_f32_e32 v91, s80, v91
	v_mul_f32_e32 v92, s80, v92
	v_mul_f32_e32 v93, s80, v93
	v_exp_f32_e32 v94, v94
	v_exp_f32_e32 v95, v95
	v_exp_f32_e32 v96, v96
	v_exp_f32_e32 v97, v97
	v_exp_f32_e32 v90, v90
	v_exp_f32_e32 v91, v91
	v_exp_f32_e32 v92, v92
	v_exp_f32_e32 v93, v93
	v_add_f32_e32 v94, 1.0, v94
	v_add_f32_e32 v95, 1.0, v95
	v_add_f32_e32 v96, 1.0, v96
	v_add_f32_e32 v97, 1.0, v97
	v_add_f32_e32 v90, 1.0, v90
	v_add_f32_e32 v91, 1.0, v91
	v_add_f32_e32 v92, 1.0, v92
	v_add_f32_e32 v93, 1.0, v93
	v_rcp_f32_e32 v94, v94
	v_rcp_f32_e32 v95, v95
	v_rcp_f32_e32 v96, v96
	v_rcp_f32_e32 v97, v97
	v_rcp_f32_e32 v90, v90
	v_rcp_f32_e32 v91, v91
	v_rcp_f32_e32 v92, v92
	v_rcp_f32_e32 v93, v93
	s_waitcnt vmcnt(16)
; __device__ __forceinline__ unsigned pk2(float lo, float hi) { return pg8::cvt_pk_bf16(lo, hi); }
; __device__ __forceinline__ float bflo(unsigned u) { return __uint_as_float(u << 16); }
; __device__ __forceinline__ float bfhi(unsigned u) { return __uint_as_float(u & 0xffff0000u); }
; __device__ __forceinline__ f32x2 sigm2(f32x2 v) { const f32x2 a = v * -1.4426950408889634f; f32x2 e; e.x = __builtin_amdgcn_exp2f(a.x); e.y = __builtin_amdgcn_exp2f(a.y); const f32x2 d = e + 1.0f; f32x2 r; r.x = __builtin_amdgcn_rcpf(d.x); r.y = __builtin_amdgcn_rcpf(d.y); return r; }
;     __device__ __forceinline__ void operator()(const pg8::f32x4 (&acc)[2][2][4][2], const Unit& u, int wr, int wc, int fr_, int fq_) const {
;     ...
;                 for (int bj = 0; bj < 2; ++bj) { const size_t off = (size_t)row * DM + col0 + bj * HALF;
;                     const u32x4 t = *(const u32x4*)(T + off); const u32x4 xb = *(const u32x4*)(XB + off);
;                     pg8::f32x4 x0 = {bflo(xb.x), bfhi(xb.x), bflo(xb.y), bfhi(xb.y)}, x1 = {bflo(xb.z), bfhi(xb.z), bflo(xb.w), bfhi(xb.w)};
;                     const pg8::f32x4 a0 = acc[ai][bj][m][0], a1 = acc[ai][bj][m][1];
;                     { const f32x2 s0 = sigm2((f32x2){a0[0], a0[1]}), s1 = sigm2((f32x2){a0[2], a0[3]}), s2 = sigm2((f32x2){a1[0], a1[1]}), s3 = sigm2((f32x2){a1[2], a1[3]});
;                       x0[0] += s0.x * bflo(t.x); x0[1] += s0.y * bfhi(t.x); x0[2] += s1.x * bflo(t.y); x0[3] += s1.y * bfhi(t.y);
;                       x1[0] += s2.x * bflo(t.z); x1[1] += s2.y * bfhi(t.z); x1[2] += s3.x * bflo(t.w); x1[3] += s3.y * bfhi(t.w); }
;                     if (f32out) { *(pg8::f32x4*)(Xo + off) = x0; *(pg8::f32x4*)(Xo + off + 4) = x1; }
;                     else { u32x4 w; w.x = pk2(x0[0], x0[1]); w.y = pk2(x0[2], x0[3]); w.z = pk2(x1[0], x1[1]); w.w = pk2(x1[2], x1[3]); *(u32x4*)((bf16_t*)Xo + off) = w; } } }
	v_lshlrev_b32_e32 v204, 16, v176
	v_lshlrev_b32_e32 v205, 16, v180
	v_and_b32_e32 v176, 0xffff0000, v176
	v_and_b32_e32 v180, 0xffff0000, v180
	v_fma_f32 v94, v94, v204, v205
	v_fma_f32 v95, v95, v176, v180
	v_lshlrev_b32_e32 v204, 16, v177
	v_lshlrev_b32_e32 v205, 16, v181
	v_and_b32_e32 v177, 0xffff0000, v177
	v_and_b32_e32 v181, 0xffff0000, v181
	v_fma_f32 v96, v96, v204, v205
	v_fma_f32 v97, v97, v177, v181
	v_lshlrev_b32_e32 v204, 16, v178
	v_lshlrev_b32_e32 v205, 16, v182
	v_and_b32_e32 v178, 0xffff0000, v178
	v_and_b32_e32 v182, 0xffff0000, v182
	v_fma_f32 v90, v90, v204, v205
	v_fma_f32 v91, v91, v178, v182
	v_lshlrev_b32_e32 v204, 16, v179
	v_lshlrev_b32_e32 v205, 16, v183
	v_and_b32_e32 v179, 0xffff0000, v179
	v_and_b32_e32 v183, 0xffff0000, v183
	v_fma_f32 v92, v92, v204, v205
	v_fma_f32 v93, v93, v179, v183
	v_cvt_pk_bf16_f32 v176, v94, v95
	v_cvt_pk_bf16_f32 v177, v96, v97
	v_cvt_pk_bf16_f32 v178, v90, v91
	v_cvt_pk_bf16_f32 v179, v92, v93
	v_add_u32_e32 v207, 0x10000, v202
	global_store_dwordx4 v207, v[176:179], s[4:5]
	v_add_u32_e32 v203, 0x48000, v202
	global_load_dwordx4 v[176:179], v203, s[6:7] offset:256
	global_load_dwordx4 v[180:183], v203, s[10:11] offset:256
	v_mul_f32_e32 v86, s80, v86
	v_mul_f32_e32 v87, s80, v87
	v_mul_f32_e32 v88, s80, v88
	v_mul_f32_e32 v89, s80, v89
	v_mul_f32_e32 v82, s80, v82
	v_mul_f32_e32 v83, s80, v83
	v_mul_f32_e32 v84, s80, v84
	v_mul_f32_e32 v85, s80, v85
	v_exp_f32_e32 v86, v86
	v_exp_f32_e32 v87, v87
	v_exp_f32_e32 v88, v88
	v_exp_f32_e32 v89, v89
	v_exp_f32_e32 v82, v82
	v_exp_f32_e32 v83, v83
	v_exp_f32_e32 v84, v84
	v_exp_f32_e32 v85, v85
	v_add_f32_e32 v86, 1.0, v86
	v_add_f32_e32 v87, 1.0, v87
	v_add_f32_e32 v88, 1.0, v88
	v_add_f32_e32 v89, 1.0, v89
	v_add_f32_e32 v82, 1.0, v82
	v_add_f32_e32 v83, 1.0, v83
	v_add_f32_e32 v84, 1.0, v84
	v_add_f32_e32 v85, 1.0, v85
	v_rcp_f32_e32 v86, v86
	v_rcp_f32_e32 v87, v87
	v_rcp_f32_e32 v88, v88
	v_rcp_f32_e32 v89, v89
	v_rcp_f32_e32 v82, v82
	v_rcp_f32_e32 v83, v83
	v_rcp_f32_e32 v84, v84
	v_rcp_f32_e32 v85, v85
	s_waitcnt vmcnt(17)
	v_lshlrev_b32_e32 v204, 16, v184
	v_lshlrev_b32_e32 v205, 16, v188
	v_and_b32_e32 v184, 0xffff0000, v184
	v_and_b32_e32 v188, 0xffff0000, v188
	v_fma_f32 v86, v86, v204, v205
	v_fma_f32 v87, v87, v184, v188
	v_lshlrev_b32_e32 v204, 16, v185
	v_lshlrev_b32_e32 v205, 16, v189
	v_and_b32_e32 v185, 0xffff0000, v185
	v_and_b32_e32 v189, 0xffff0000, v189
	v_fma_f32 v88, v88, v204, v205
	v_fma_f32 v89, v89, v185, v189
	v_lshlrev_b32_e32 v204, 16, v186
	v_lshlrev_b32_e32 v205, 16, v190
	v_and_b32_e32 v186, 0xffff0000, v186
	v_and_b32_e32 v190, 0xffff0000, v190
	v_fma_f32 v82, v82, v204, v205
	v_fma_f32 v83, v83, v186, v190
	v_lshlrev_b32_e32 v204, 16, v187
	v_lshlrev_b32_e32 v205, 16, v191
	v_and_b32_e32 v187, 0xffff0000, v187
	v_and_b32_e32 v191, 0xffff0000, v191
	v_fma_f32 v84, v84, v204, v205
	v_fma_f32 v85, v85, v187, v191
	v_cvt_pk_bf16_f32 v184, v86, v87
	v_cvt_pk_bf16_f32 v185, v88, v89
	v_cvt_pk_bf16_f32 v186, v82, v83
	v_cvt_pk_bf16_f32 v187, v84, v85
	v_add_u32_e32 v207, 0x10000, v202
	global_store_dwordx4 v207, v[184:187], s[4:5] offset:256
	v_add_u32_e32 v203, 0x50000, v202
	global_load_dwordx4 v[184:187], v203, s[6:7]
	global_load_dwordx4 v[188:191], v203, s[10:11]
	v_mul_f32_e32 v78, s80, v78
	v_mul_f32_e32 v79, s80, v79
	v_mul_f32_e32 v80, s80, v80
	v_mul_f32_e32 v81, s80, v81
	v_mul_f32_e32 v74, s80, v74
	v_mul_f32_e32 v75, s80, v75
	v_mul_f32_e32 v76, s80, v76
	v_mul_f32_e32 v77, s80, v77
	v_exp_f32_e32 v78, v78
	v_exp_f32_e32 v79, v79
	v_exp_f32_e32 v80, v80
	v_exp_f32_e32 v81, v81
	v_exp_f32_e32 v74, v74
	v_exp_f32_e32 v75, v75
	v_exp_f32_e32 v76, v76
	v_exp_f32_e32 v77, v77
	v_add_f32_e32 v78, 1.0, v78
	v_add_f32_e32 v79, 1.0, v79
	v_add_f32_e32 v80, 1.0, v80
	v_add_f32_e32 v81, 1.0, v81
	v_add_f32_e32 v74, 1.0, v74
	v_add_f32_e32 v75, 1.0, v75
	v_add_f32_e32 v76, 1.0, v76
	v_add_f32_e32 v77, 1.0, v77
	v_rcp_f32_e32 v78, v78
	v_rcp_f32_e32 v79, v79
	v_rcp_f32_e32 v80, v80
	v_rcp_f32_e32 v81, v81
	v_rcp_f32_e32 v74, v74
	v_rcp_f32_e32 v75, v75
	v_rcp_f32_e32 v76, v76
	v_rcp_f32_e32 v77, v77
	s_waitcnt vmcnt(18)
	v_lshlrev_b32_e32 v204, 16, v192
	v_lshlrev_b32_e32 v205, 16, v196
	v_and_b32_e32 v192, 0xffff0000, v192
	v_and_b32_e32 v196, 0xffff0000, v196
	v_fma_f32 v78, v78, v204, v205
	v_fma_f32 v79, v79, v192, v196
	v_lshlrev_b32_e32 v204, 16, v193
	v_lshlrev_b32_e32 v205, 16, v197
	v_and_b32_e32 v193, 0xffff0000, v193
	v_and_b32_e32 v197, 0xffff0000, v197
	v_fma_f32 v80, v80, v204, v205
	v_fma_f32 v81, v81, v193, v197
	v_lshlrev_b32_e32 v204, 16, v194
	v_lshlrev_b32_e32 v205, 16, v198
	v_and_b32_e32 v194, 0xffff0000, v194
	v_and_b32_e32 v198, 0xffff0000, v198
	v_fma_f32 v74, v74, v204, v205
	v_fma_f32 v75, v75, v194, v198
	v_lshlrev_b32_e32 v204, 16, v195
	v_lshlrev_b32_e32 v205, 16, v199
	v_and_b32_e32 v195, 0xffff0000, v195
	v_and_b32_e32 v199, 0xffff0000, v199
	v_fma_f32 v76, v76, v204, v205
	v_fma_f32 v77, v77, v195, v199
	v_cvt_pk_bf16_f32 v192, v78, v79
	v_cvt_pk_bf16_f32 v193, v80, v81
	v_cvt_pk_bf16_f32 v194, v74, v75
	v_cvt_pk_bf16_f32 v195, v76, v77
	v_add_u32_e32 v207, 0x18000, v202
	global_store_dwordx4 v207, v[192:195], s[4:5]
	v_add_u32_e32 v203, 0x50000, v202
	global_load_dwordx4 v[192:195], v203, s[6:7] offset:256
	global_load_dwordx4 v[196:199], v203, s[10:11] offset:256
	v_mul_f32_e32 v70, s80, v70
	v_mul_f32_e32 v71, s80, v71
	v_mul_f32_e32 v72, s80, v72
	v_mul_f32_e32 v73, s80, v73
	v_mul_f32_e32 v66, s80, v66
	v_mul_f32_e32 v67, s80, v67
	v_mul_f32_e32 v68, s80, v68
	v_mul_f32_e32 v69, s80, v69
	v_exp_f32_e32 v70, v70
	v_exp_f32_e32 v71, v71
	v_exp_f32_e32 v72, v72
	v_exp_f32_e32 v73, v73
	v_exp_f32_e32 v66, v66
	v_exp_f32_e32 v67, v67
	v_exp_f32_e32 v68, v68
	v_exp_f32_e32 v69, v69
	v_add_f32_e32 v70, 1.0, v70
	v_add_f32_e32 v71, 1.0, v71
	v_add_f32_e32 v72, 1.0, v72
	v_add_f32_e32 v73, 1.0, v73
	v_add_f32_e32 v66, 1.0, v66
	v_add_f32_e32 v67, 1.0, v67
	v_add_f32_e32 v68, 1.0, v68
	v_add_f32_e32 v69, 1.0, v69
	v_rcp_f32_e32 v70, v70
	v_rcp_f32_e32 v71, v71
	v_rcp_f32_e32 v72, v72
	v_rcp_f32_e32 v73, v73
	v_rcp_f32_e32 v66, v66
	v_rcp_f32_e32 v67, v67
	v_rcp_f32_e32 v68, v68
	v_rcp_f32_e32 v69, v69
	s_waitcnt vmcnt(18)
; __device__ __forceinline__ unsigned pk2(float lo, float hi) { return pg8::cvt_pk_bf16(lo, hi); }
; __device__ __forceinline__ float bflo(unsigned u) { return __uint_as_float(u << 16); }
; __device__ __forceinline__ float bfhi(unsigned u) { return __uint_as_float(u & 0xffff0000u); }
; __device__ __forceinline__ f32x2 sigm2(f32x2 v) { const f32x2 a = v * -1.4426950408889634f; f32x2 e; e.x = __builtin_amdgcn_exp2f(a.x); e.y = __builtin_amdgcn_exp2f(a.y); const f32x2 d = e + 1.0f; f32x2 r; r.x = __builtin_amdgcn_rcpf(d.x); r.y = __builtin_amdgcn_rcpf(d.y); return r; }
;     __device__ __forceinline__ void operator()(const pg8::f32x4 (&acc)[2][2][4][2], const Unit& u, int wr, int wc, int fr_, int fq_) const {
;     ...
;                 for (int bj = 0; bj < 2; ++bj) { const size_t off = (size_t)row * DM + col0 + bj * HALF;
;                     const u32x4 t = *(const u32x4*)(T + off); const u32x4 xb = *(const u32x4*)(XB + off);
;                     pg8::f32x4 x0 = {bflo(xb.x), bfhi(xb.x), bflo(xb.y), bfhi(xb.y)}, x1 = {bflo(xb.z), bfhi(xb.z), bflo(xb.w), bfhi(xb.w)};
;                     const pg8::f32x4 a0 = acc[ai][bj][m][0], a1 = acc[ai][bj][m][1];
;                     { const f32x2 s0 = sigm2((f32x2){a0[0], a0[1]}), s1 = sigm2((f32x2){a0[2], a0[3]}), s2 = sigm2((f32x2){a1[0], a1[1]}), s3 = sigm2((f32x2){a1[2], a1[3]});
;                       x0[0] += s0.x * bflo(t.x); x0[1] += s0.y * bfhi(t.x); x0[2] += s1.x * bflo(t.y); x0[3] += s1.y * bfhi(t.y);
;                       x1[0] += s2.x * bflo(t.z); x1[1] += s2.y * bfhi(t.z); x1[2] += s3.x * bflo(t.w); x1[3] += s3.y * bfhi(t.w); }
;                     if (f32out) { *(pg8::f32x4*)(Xo + off) = x0; *(pg8::f32x4*)(Xo + off + 4) = x1; }
;                     else { u32x4 w; w.x = pk2(x0[0], x0[1]); w.y = pk2(x0[2], x0[3]); w.z = pk2(x1[0], x1[1]); w.w = pk2(x1[2], x1[3]); *(u32x4*)((bf16_t*)Xo + off) = w; } } }
	v_lshlrev_b32_e32 v204, 16, v140
	v_lshlrev_b32_e32 v205, 16, v144
	v_and_b32_e32 v140, 0xffff0000, v140
	v_and_b32_e32 v144, 0xffff0000, v144
	v_fma_f32 v70, v70, v204, v205
	v_fma_f32 v71, v71, v140, v144
	v_lshlrev_b32_e32 v204, 16, v141
	v_lshlrev_b32_e32 v205, 16, v145
	v_and_b32_e32 v141, 0xffff0000, v141
	v_and_b32_e32 v145, 0xffff0000, v145
	v_fma_f32 v72, v72, v204, v205
	v_fma_f32 v73, v73, v141, v145
	v_lshlrev_b32_e32 v204, 16, v142
	v_lshlrev_b32_e32 v205, 16, v146
	v_and_b32_e32 v142, 0xffff0000, v142
	v_and_b32_e32 v146, 0xffff0000, v146
	v_fma_f32 v66, v66, v204, v205
	v_fma_f32 v67, v67, v142, v146
	v_lshlrev_b32_e32 v204, 16, v143
	v_lshlrev_b32_e32 v205, 16, v147
	v_and_b32_e32 v143, 0xffff0000, v143
	v_and_b32_e32 v147, 0xffff0000, v147
	v_fma_f32 v68, v68, v204, v205
	v_fma_f32 v69, v69, v143, v147
	v_cvt_pk_bf16_f32 v140, v70, v71
	v_cvt_pk_bf16_f32 v141, v72, v73
	v_cvt_pk_bf16_f32 v142, v66, v67
	v_cvt_pk_bf16_f32 v143, v68, v69
	v_add_u32_e32 v207, 0x18000, v202
	global_store_dwordx4 v207, v[140:143], s[4:5] offset:256
	v_add_u32_e32 v203, 0x58000, v202
	global_load_dwordx4 v[140:143], v203, s[6:7]
	global_load_dwordx4 v[144:147], v203, s[10:11]
	v_mul_f32_e32 v62, s80, v62
	v_mul_f32_e32 v63, s80, v63
	v_mul_f32_e32 v64, s80, v64
	v_mul_f32_e32 v65, s80, v65
	v_mul_f32_e32 v58, s80, v58
	v_mul_f32_e32 v59, s80, v59
	v_mul_f32_e32 v60, s80, v60
	v_mul_f32_e32 v61, s80, v61
	v_exp_f32_e32 v62, v62
	v_exp_f32_e32 v63, v63
	v_exp_f32_e32 v64, v64
	v_exp_f32_e32 v65, v65
	v_exp_f32_e32 v58, v58
	v_exp_f32_e32 v59, v59
	v_exp_f32_e32 v60, v60
	v_exp_f32_e32 v61, v61
	v_add_f32_e32 v62, 1.0, v62
	v_add_f32_e32 v63, 1.0, v63
	v_add_f32_e32 v64, 1.0, v64
	v_add_f32_e32 v65, 1.0, v65
	v_add_f32_e32 v58, 1.0, v58
	v_add_f32_e32 v59, 1.0, v59
	v_add_f32_e32 v60, 1.0, v60
	v_add_f32_e32 v61, 1.0, v61
	v_rcp_f32_e32 v62, v62
	v_rcp_f32_e32 v63, v63
	v_rcp_f32_e32 v64, v64
	v_rcp_f32_e32 v65, v65
	v_rcp_f32_e32 v58, v58
	v_rcp_f32_e32 v59, v59
	v_rcp_f32_e32 v60, v60
	v_rcp_f32_e32 v61, v61
	s_waitcnt vmcnt(18)
	v_lshlrev_b32_e32 v204, 16, v152
	v_lshlrev_b32_e32 v205, 16, v156
	v_and_b32_e32 v152, 0xffff0000, v152
	v_and_b32_e32 v156, 0xffff0000, v156
	v_fma_f32 v62, v62, v204, v205
	v_fma_f32 v63, v63, v152, v156
	v_lshlrev_b32_e32 v204, 16, v153
	v_lshlrev_b32_e32 v205, 16, v157
	v_and_b32_e32 v153, 0xffff0000, v153
	v_and_b32_e32 v157, 0xffff0000, v157
	v_fma_f32 v64, v64, v204, v205
	v_fma_f32 v65, v65, v153, v157
	v_lshlrev_b32_e32 v204, 16, v154
	v_lshlrev_b32_e32 v205, 16, v158
	v_and_b32_e32 v154, 0xffff0000, v154
	v_and_b32_e32 v158, 0xffff0000, v158
	v_fma_f32 v58, v58, v204, v205
	v_fma_f32 v59, v59, v154, v158
	v_lshlrev_b32_e32 v204, 16, v155
	v_lshlrev_b32_e32 v205, 16, v159
	v_and_b32_e32 v155, 0xffff0000, v155
	v_and_b32_e32 v159, 0xffff0000, v159
	v_fma_f32 v60, v60, v204, v205
	v_fma_f32 v61, v61, v155, v159
	v_cvt_pk_bf16_f32 v152, v62, v63
	v_cvt_pk_bf16_f32 v153, v64, v65
	v_cvt_pk_bf16_f32 v154, v58, v59
	v_cvt_pk_bf16_f32 v155, v60, v61
	v_add_u32_e32 v207, 0x40000, v202
	global_store_dwordx4 v207, v[152:155], s[4:5]
	v_add_u32_e32 v203, 0x58000, v202
	global_load_dwordx4 v[152:155], v203, s[6:7] offset:256
	global_load_dwordx4 v[156:159], v203, s[10:11] offset:256
	v_mul_f32_e32 v54, s80, v54
	v_mul_f32_e32 v55, s80, v55
	v_mul_f32_e32 v56, s80, v56
	v_mul_f32_e32 v57, s80, v57
	v_mul_f32_e32 v50, s80, v50
	v_mul_f32_e32 v51, s80, v51
	v_mul_f32_e32 v52, s80, v52
	v_mul_f32_e32 v53, s80, v53
	v_exp_f32_e32 v54, v54
	v_exp_f32_e32 v55, v55
	v_exp_f32_e32 v56, v56
	v_exp_f32_e32 v57, v57
	v_exp_f32_e32 v50, v50
	v_exp_f32_e32 v51, v51
	v_exp_f32_e32 v52, v52
	v_exp_f32_e32 v53, v53
	v_add_f32_e32 v54, 1.0, v54
	v_add_f32_e32 v55, 1.0, v55
	v_add_f32_e32 v56, 1.0, v56
	v_add_f32_e32 v57, 1.0, v57
	v_add_f32_e32 v50, 1.0, v50
	v_add_f32_e32 v51, 1.0, v51
	v_add_f32_e32 v52, 1.0, v52
	v_add_f32_e32 v53, 1.0, v53
	v_rcp_f32_e32 v54, v54
	v_rcp_f32_e32 v55, v55
	v_rcp_f32_e32 v56, v56
	v_rcp_f32_e32 v57, v57
	v_rcp_f32_e32 v50, v50
	v_rcp_f32_e32 v51, v51
	v_rcp_f32_e32 v52, v52
	v_rcp_f32_e32 v53, v53
	s_waitcnt vmcnt(18)
	v_lshlrev_b32_e32 v204, 16, v160
	v_lshlrev_b32_e32 v205, 16, v164
	v_and_b32_e32 v160, 0xffff0000, v160
	v_and_b32_e32 v164, 0xffff0000, v164
	v_fma_f32 v54, v54, v204, v205
	v_fma_f32 v55, v55, v160, v164
	v_lshlrev_b32_e32 v204, 16, v161
	v_lshlrev_b32_e32 v205, 16, v165
	v_and_b32_e32 v161, 0xffff0000, v161
	v_and_b32_e32 v165, 0xffff0000, v165
	v_fma_f32 v56, v56, v204, v205
	v_fma_f32 v57, v57, v161, v165
	v_lshlrev_b32_e32 v204, 16, v162
	v_lshlrev_b32_e32 v205, 16, v166
	v_and_b32_e32 v162, 0xffff0000, v162
	v_and_b32_e32 v166, 0xffff0000, v166
	v_fma_f32 v50, v50, v204, v205
	v_fma_f32 v51, v51, v162, v166
	v_lshlrev_b32_e32 v204, 16, v163
	v_lshlrev_b32_e32 v205, 16, v167
	v_and_b32_e32 v163, 0xffff0000, v163
	v_and_b32_e32 v167, 0xffff0000, v167
	v_fma_f32 v52, v52, v204, v205
	v_fma_f32 v53, v53, v163, v167
	v_cvt_pk_bf16_f32 v160, v54, v55
	v_cvt_pk_bf16_f32 v161, v56, v57
	v_cvt_pk_bf16_f32 v162, v50, v51
	v_cvt_pk_bf16_f32 v163, v52, v53
	v_add_u32_e32 v207, 0x40000, v202
	global_store_dwordx4 v207, v[160:163], s[4:5] offset:256
	v_mul_f32_e32 v46, s80, v46
	v_mul_f32_e32 v47, s80, v47
	v_mul_f32_e32 v48, s80, v48
	v_mul_f32_e32 v49, s80, v49
	v_mul_f32_e32 v42, s80, v42
	v_mul_f32_e32 v43, s80, v43
	v_mul_f32_e32 v44, s80, v44
	v_mul_f32_e32 v45, s80, v45
	v_exp_f32_e32 v46, v46
	v_exp_f32_e32 v47, v47
	v_exp_f32_e32 v48, v48
	v_exp_f32_e32 v49, v49
	v_exp_f32_e32 v42, v42
	v_exp_f32_e32 v43, v43
	v_exp_f32_e32 v44, v44
	v_exp_f32_e32 v45, v45
	v_add_f32_e32 v46, 1.0, v46
	v_add_f32_e32 v47, 1.0, v47
	v_add_f32_e32 v48, 1.0, v48
	v_add_f32_e32 v49, 1.0, v49
	v_add_f32_e32 v42, 1.0, v42
	v_add_f32_e32 v43, 1.0, v43
	v_add_f32_e32 v44, 1.0, v44
	v_add_f32_e32 v45, 1.0, v45
	v_rcp_f32_e32 v46, v46
	v_rcp_f32_e32 v47, v47
	v_rcp_f32_e32 v48, v48
	v_rcp_f32_e32 v49, v49
	v_rcp_f32_e32 v42, v42
	v_rcp_f32_e32 v43, v43
	v_rcp_f32_e32 v44, v44
	v_rcp_f32_e32 v45, v45
	s_waitcnt vmcnt(16)
; __device__ __forceinline__ unsigned pk2(float lo, float hi) { return pg8::cvt_pk_bf16(lo, hi); }
; __device__ __forceinline__ float bflo(unsigned u) { return __uint_as_float(u << 16); }
; __device__ __forceinline__ float bfhi(unsigned u) { return __uint_as_float(u & 0xffff0000u); }
; __device__ __forceinline__ f32x2 sigm2(f32x2 v) { const f32x2 a = v * -1.4426950408889634f; f32x2 e; e.x = __builtin_amdgcn_exp2f(a.x); e.y = __builtin_amdgcn_exp2f(a.y); const f32x2 d = e + 1.0f; f32x2 r; r.x = __builtin_amdgcn_rcpf(d.x); r.y = __builtin_amdgcn_rcpf(d.y); return r; }
;     __device__ __forceinline__ void operator()(const pg8::f32x4 (&acc)[2][2][4][2], const Unit& u, int wr, int wc, int fr_, int fq_) const {
;     ...
;                 for (int bj = 0; bj < 2; ++bj) { const size_t off = (size_t)row * DM + col0 + bj * HALF;
;                     const u32x4 t = *(const u32x4*)(T + off); const u32x4 xb = *(const u32x4*)(XB + off);
;                     pg8::f32x4 x0 = {bflo(xb.x), bfhi(xb.x), bflo(xb.y), bfhi(xb.y)}, x1 = {bflo(xb.z), bfhi(xb.z), bflo(xb.w), bfhi(xb.w)};
;                     const pg8::f32x4 a0 = acc[ai][bj][m][0], a1 = acc[ai][bj][m][1];
;                     { const f32x2 s0 = sigm2((f32x2){a0[0], a0[1]}), s1 = sigm2((f32x2){a0[2], a0[3]}), s2 = sigm2((f32x2){a1[0], a1[1]}), s3 = sigm2((f32x2){a1[2], a1[3]});
;                       x0[0] += s0.x * bflo(t.x); x0[1] += s0.y * bfhi(t.x); x0[2] += s1.x * bflo(t.y); x0[3] += s1.y * bfhi(t.y);
;                       x1[0] += s2.x * bflo(t.z); x1[1] += s2.y * bfhi(t.z); x1[2] += s3.x * bflo(t.w); x1[3] += s3.y * bfhi(t.w); }
;                     if (f32out) { *(pg8::f32x4*)(Xo + off) = x0; *(pg8::f32x4*)(Xo + off + 4) = x1; }
;                     else { u32x4 w; w.x = pk2(x0[0], x0[1]); w.y = pk2(x0[2], x0[3]); w.z = pk2(x1[0], x1[1]); w.w = pk2(x1[2], x1[3]); *(u32x4*)((bf16_t*)Xo + off) = w; } } }
	v_lshlrev_b32_e32 v204, 16, v168
	v_lshlrev_b32_e32 v205, 16, v172
	v_and_b32_e32 v168, 0xffff0000, v168
	v_and_b32_e32 v172, 0xffff0000, v172
	v_fma_f32 v46, v46, v204, v205
	v_fma_f32 v47, v47, v168, v172
	v_lshlrev_b32_e32 v204, 16, v169
	v_lshlrev_b32_e32 v205, 16, v173
	v_and_b32_e32 v169, 0xffff0000, v169
	v_and_b32_e32 v173, 0xffff0000, v173
	v_fma_f32 v48, v48, v204, v205
	v_fma_f32 v49, v49, v169, v173
	v_lshlrev_b32_e32 v204, 16, v170
	v_lshlrev_b32_e32 v205, 16, v174
	v_and_b32_e32 v170, 0xffff0000, v170
	v_and_b32_e32 v174, 0xffff0000, v174
	v_fma_f32 v42, v42, v204, v205
	v_fma_f32 v43, v43, v170, v174
	v_lshlrev_b32_e32 v204, 16, v171
	v_lshlrev_b32_e32 v205, 16, v175
	v_and_b32_e32 v171, 0xffff0000, v171
	v_and_b32_e32 v175, 0xffff0000, v175
	v_fma_f32 v44, v44, v204, v205
	v_fma_f32 v45, v45, v171, v175
	v_cvt_pk_bf16_f32 v168, v46, v47
	v_cvt_pk_bf16_f32 v169, v48, v49
	v_cvt_pk_bf16_f32 v170, v42, v43
	v_cvt_pk_bf16_f32 v171, v44, v45
	v_add_u32_e32 v207, 0x48000, v202
	global_store_dwordx4 v207, v[168:171], s[4:5]
	v_mul_f32_e32 v38, s80, v38
	v_mul_f32_e32 v39, s80, v39
	v_mul_f32_e32 v40, s80, v40
	v_mul_f32_e32 v41, s80, v41
	v_mul_f32_e32 v34, s80, v34
	v_mul_f32_e32 v35, s80, v35
	v_mul_f32_e32 v36, s80, v36
	v_mul_f32_e32 v37, s80, v37
	v_exp_f32_e32 v38, v38
	v_exp_f32_e32 v39, v39
	v_exp_f32_e32 v40, v40
	v_exp_f32_e32 v41, v41
	v_exp_f32_e32 v34, v34
	v_exp_f32_e32 v35, v35
	v_exp_f32_e32 v36, v36
	v_exp_f32_e32 v37, v37
	v_add_f32_e32 v38, 1.0, v38
	v_add_f32_e32 v39, 1.0, v39
	v_add_f32_e32 v40, 1.0, v40
	v_add_f32_e32 v41, 1.0, v41
	v_add_f32_e32 v34, 1.0, v34
	v_add_f32_e32 v35, 1.0, v35
	v_add_f32_e32 v36, 1.0, v36
	v_add_f32_e32 v37, 1.0, v37
	v_rcp_f32_e32 v38, v38
	v_rcp_f32_e32 v39, v39
	v_rcp_f32_e32 v40, v40
	v_rcp_f32_e32 v41, v41
	v_rcp_f32_e32 v34, v34
	v_rcp_f32_e32 v35, v35
	v_rcp_f32_e32 v36, v36
	v_rcp_f32_e32 v37, v37
	s_waitcnt vmcnt(14)
	v_lshlrev_b32_e32 v204, 16, v176
	v_lshlrev_b32_e32 v205, 16, v180
	v_and_b32_e32 v176, 0xffff0000, v176
	v_and_b32_e32 v180, 0xffff0000, v180
	v_fma_f32 v38, v38, v204, v205
	v_fma_f32 v39, v39, v176, v180
	v_lshlrev_b32_e32 v204, 16, v177
	v_lshlrev_b32_e32 v205, 16, v181
	v_and_b32_e32 v177, 0xffff0000, v177
	v_and_b32_e32 v181, 0xffff0000, v181
	v_fma_f32 v40, v40, v204, v205
	v_fma_f32 v41, v41, v177, v181
	v_lshlrev_b32_e32 v204, 16, v178
	v_lshlrev_b32_e32 v205, 16, v182
	v_and_b32_e32 v178, 0xffff0000, v178
	v_and_b32_e32 v182, 0xffff0000, v182
	v_fma_f32 v34, v34, v204, v205
	v_fma_f32 v35, v35, v178, v182
	v_lshlrev_b32_e32 v204, 16, v179
	v_lshlrev_b32_e32 v205, 16, v183
	v_and_b32_e32 v179, 0xffff0000, v179
	v_and_b32_e32 v183, 0xffff0000, v183
	v_fma_f32 v36, v36, v204, v205
	v_fma_f32 v37, v37, v179, v183
	v_cvt_pk_bf16_f32 v176, v38, v39
	v_cvt_pk_bf16_f32 v177, v40, v41
	v_cvt_pk_bf16_f32 v178, v34, v35
	v_cvt_pk_bf16_f32 v179, v36, v37
	v_add_u32_e32 v207, 0x48000, v202
	global_store_dwordx4 v207, v[176:179], s[4:5] offset:256
	v_mul_f32_e32 v30, s80, v30
	v_mul_f32_e32 v31, s80, v31
	v_mul_f32_e32 v32, s80, v32
	v_mul_f32_e32 v33, s80, v33
	v_mul_f32_e32 v26, s80, v26
	v_mul_f32_e32 v27, s80, v27
	v_mul_f32_e32 v28, s80, v28
	v_mul_f32_e32 v29, s80, v29
	v_exp_f32_e32 v30, v30
	v_exp_f32_e32 v31, v31
	v_exp_f32_e32 v32, v32
	v_exp_f32_e32 v33, v33
	v_exp_f32_e32 v26, v26
	v_exp_f32_e32 v27, v27
	v_exp_f32_e32 v28, v28
	v_exp_f32_e32 v29, v29
	v_add_f32_e32 v30, 1.0, v30
	v_add_f32_e32 v31, 1.0, v31
	v_add_f32_e32 v32, 1.0, v32
	v_add_f32_e32 v33, 1.0, v33
	v_add_f32_e32 v26, 1.0, v26
	v_add_f32_e32 v27, 1.0, v27
	v_add_f32_e32 v28, 1.0, v28
	v_add_f32_e32 v29, 1.0, v29
	v_rcp_f32_e32 v30, v30
	v_rcp_f32_e32 v31, v31
	v_rcp_f32_e32 v32, v32
	v_rcp_f32_e32 v33, v33
	v_rcp_f32_e32 v26, v26
	v_rcp_f32_e32 v27, v27
	v_rcp_f32_e32 v28, v28
	v_rcp_f32_e32 v29, v29
	s_waitcnt vmcnt(12)
	v_lshlrev_b32_e32 v204, 16, v184
	v_lshlrev_b32_e32 v205, 16, v188
	v_and_b32_e32 v184, 0xffff0000, v184
	v_and_b32_e32 v188, 0xffff0000, v188
	v_fma_f32 v30, v30, v204, v205
	v_fma_f32 v31, v31, v184, v188
	v_lshlrev_b32_e32 v204, 16, v185
	v_lshlrev_b32_e32 v205, 16, v189
	v_and_b32_e32 v185, 0xffff0000, v185
	v_and_b32_e32 v189, 0xffff0000, v189
	v_fma_f32 v32, v32, v204, v205
	v_fma_f32 v33, v33, v185, v189
	v_lshlrev_b32_e32 v204, 16, v186
	v_lshlrev_b32_e32 v205, 16, v190
	v_and_b32_e32 v186, 0xffff0000, v186
	v_and_b32_e32 v190, 0xffff0000, v190
	v_fma_f32 v26, v26, v204, v205
	v_fma_f32 v27, v27, v186, v190
	v_lshlrev_b32_e32 v204, 16, v187
	v_lshlrev_b32_e32 v205, 16, v191
	v_and_b32_e32 v187, 0xffff0000, v187
	v_and_b32_e32 v191, 0xffff0000, v191
	v_fma_f32 v28, v28, v204, v205
	v_fma_f32 v29, v29, v187, v191
	v_cvt_pk_bf16_f32 v184, v30, v31
	v_cvt_pk_bf16_f32 v185, v32, v33
	v_cvt_pk_bf16_f32 v186, v26, v27
	v_cvt_pk_bf16_f32 v187, v28, v29
	v_add_u32_e32 v207, 0x50000, v202
	global_store_dwordx4 v207, v[184:187], s[4:5]
	v_mul_f32_e32 v22, s80, v22
	v_mul_f32_e32 v23, s80, v23
	v_mul_f32_e32 v24, s80, v24
	v_mul_f32_e32 v25, s80, v25
	v_mul_f32_e32 v18, s80, v18
	v_mul_f32_e32 v19, s80, v19
	v_mul_f32_e32 v20, s80, v20
	v_mul_f32_e32 v21, s80, v21
	v_exp_f32_e32 v22, v22
	v_exp_f32_e32 v23, v23
	v_exp_f32_e32 v24, v24
	v_exp_f32_e32 v25, v25
	v_exp_f32_e32 v18, v18
	v_exp_f32_e32 v19, v19
	v_exp_f32_e32 v20, v20
	v_exp_f32_e32 v21, v21
	v_add_f32_e32 v22, 1.0, v22
	v_add_f32_e32 v23, 1.0, v23
	v_add_f32_e32 v24, 1.0, v24
	v_add_f32_e32 v25, 1.0, v25
	v_add_f32_e32 v18, 1.0, v18
	v_add_f32_e32 v19, 1.0, v19
	v_add_f32_e32 v20, 1.0, v20
	v_add_f32_e32 v21, 1.0, v21
	v_rcp_f32_e32 v22, v22
	v_rcp_f32_e32 v23, v23
	v_rcp_f32_e32 v24, v24
	v_rcp_f32_e32 v25, v25
	v_rcp_f32_e32 v18, v18
	v_rcp_f32_e32 v19, v19
	v_rcp_f32_e32 v20, v20
	v_rcp_f32_e32 v21, v21
	s_waitcnt vmcnt(10)
; __device__ __forceinline__ unsigned pk2(float lo, float hi) { return pg8::cvt_pk_bf16(lo, hi); }
; __device__ __forceinline__ float bflo(unsigned u) { return __uint_as_float(u << 16); }
; __device__ __forceinline__ float bfhi(unsigned u) { return __uint_as_float(u & 0xffff0000u); }
; __device__ __forceinline__ f32x2 sigm2(f32x2 v) { const f32x2 a = v * -1.4426950408889634f; f32x2 e; e.x = __builtin_amdgcn_exp2f(a.x); e.y = __builtin_amdgcn_exp2f(a.y); const f32x2 d = e + 1.0f; f32x2 r; r.x = __builtin_amdgcn_rcpf(d.x); r.y = __builtin_amdgcn_rcpf(d.y); return r; }
;     __device__ __forceinline__ void operator()(const pg8::f32x4 (&acc)[2][2][4][2], const Unit& u, int wr, int wc, int fr_, int fq_) const {
;     ...
;                 for (int bj = 0; bj < 2; ++bj) { const size_t off = (size_t)row * DM + col0 + bj * HALF;
;                     const u32x4 t = *(const u32x4*)(T + off); const u32x4 xb = *(const u32x4*)(XB + off);
;                     pg8::f32x4 x0 = {bflo(xb.x), bfhi(xb.x), bflo(xb.y), bfhi(xb.y)}, x1 = {bflo(xb.z), bfhi(xb.z), bflo(xb.w), bfhi(xb.w)};
;                     const pg8::f32x4 a0 = acc[ai][bj][m][0], a1 = acc[ai][bj][m][1];
;                     { const f32x2 s0 = sigm2((f32x2){a0[0], a0[1]}), s1 = sigm2((f32x2){a0[2], a0[3]}), s2 = sigm2((f32x2){a1[0], a1[1]}), s3 = sigm2((f32x2){a1[2], a1[3]});
;                       x0[0] += s0.x * bflo(t.x); x0[1] += s0.y * bfhi(t.x); x0[2] += s1.x * bflo(t.y); x0[3] += s1.y * bfhi(t.y);
;                       x1[0] += s2.x * bflo(t.z); x1[1] += s2.y * bfhi(t.z); x1[2] += s3.x * bflo(t.w); x1[3] += s3.y * bfhi(t.w); }
;                     if (f32out) { *(pg8::f32x4*)(Xo + off) = x0; *(pg8::f32x4*)(Xo + off + 4) = x1; }
;                     else { u32x4 w; w.x = pk2(x0[0], x0[1]); w.y = pk2(x0[2], x0[3]); w.z = pk2(x1[0], x1[1]); w.w = pk2(x1[2], x1[3]); *(u32x4*)((bf16_t*)Xo + off) = w; } } }
	v_lshlrev_b32_e32 v204, 16, v192
	v_lshlrev_b32_e32 v205, 16, v196
	v_and_b32_e32 v192, 0xffff0000, v192
	v_and_b32_e32 v196, 0xffff0000, v196
	v_fma_f32 v22, v22, v204, v205
	v_fma_f32 v23, v23, v192, v196
	v_lshlrev_b32_e32 v204, 16, v193
	v_lshlrev_b32_e32 v205, 16, v197
	v_and_b32_e32 v193, 0xffff0000, v193
	v_and_b32_e32 v197, 0xffff0000, v197
	v_fma_f32 v24, v24, v204, v205
	v_fma_f32 v25, v25, v193, v197
	v_lshlrev_b32_e32 v204, 16, v194
	v_lshlrev_b32_e32 v205, 16, v198
	v_and_b32_e32 v194, 0xffff0000, v194
	v_and_b32_e32 v198, 0xffff0000, v198
	v_fma_f32 v18, v18, v204, v205
	v_fma_f32 v19, v19, v194, v198
	v_lshlrev_b32_e32 v204, 16, v195
	v_lshlrev_b32_e32 v205, 16, v199
	v_and_b32_e32 v195, 0xffff0000, v195
	v_and_b32_e32 v199, 0xffff0000, v199
	v_fma_f32 v20, v20, v204, v205
	v_fma_f32 v21, v21, v195, v199
	v_cvt_pk_bf16_f32 v192, v22, v23
	v_cvt_pk_bf16_f32 v193, v24, v25
	v_cvt_pk_bf16_f32 v194, v18, v19
	v_cvt_pk_bf16_f32 v195, v20, v21
	v_add_u32_e32 v207, 0x50000, v202
	global_store_dwordx4 v207, v[192:195], s[4:5] offset:256
	v_mul_f32_e32 v14, s80, v14
	v_mul_f32_e32 v15, s80, v15
	v_mul_f32_e32 v16, s80, v16
	v_mul_f32_e32 v17, s80, v17
	v_mul_f32_e32 v10, s80, v10
	v_mul_f32_e32 v11, s80, v11
	v_mul_f32_e32 v12, s80, v12
	v_mul_f32_e32 v13, s80, v13
	v_exp_f32_e32 v14, v14
	v_exp_f32_e32 v15, v15
	v_exp_f32_e32 v16, v16
	v_exp_f32_e32 v17, v17
	v_exp_f32_e32 v10, v10
	v_exp_f32_e32 v11, v11
	v_exp_f32_e32 v12, v12
	v_exp_f32_e32 v13, v13
	v_add_f32_e32 v14, 1.0, v14
	v_add_f32_e32 v15, 1.0, v15
	v_add_f32_e32 v16, 1.0, v16
	v_add_f32_e32 v17, 1.0, v17
	v_add_f32_e32 v10, 1.0, v10
	v_add_f32_e32 v11, 1.0, v11
	v_add_f32_e32 v12, 1.0, v12
	v_add_f32_e32 v13, 1.0, v13
	v_rcp_f32_e32 v14, v14
	v_rcp_f32_e32 v15, v15
	v_rcp_f32_e32 v16, v16
	v_rcp_f32_e32 v17, v17
	v_rcp_f32_e32 v10, v10
	v_rcp_f32_e32 v11, v11
	v_rcp_f32_e32 v12, v12
	v_rcp_f32_e32 v13, v13
	s_waitcnt vmcnt(8)
	v_lshlrev_b32_e32 v204, 16, v140
	v_lshlrev_b32_e32 v205, 16, v144
	v_and_b32_e32 v140, 0xffff0000, v140
	v_and_b32_e32 v144, 0xffff0000, v144
	v_fma_f32 v14, v14, v204, v205
	v_fma_f32 v15, v15, v140, v144
	v_lshlrev_b32_e32 v204, 16, v141
	v_lshlrev_b32_e32 v205, 16, v145
	v_and_b32_e32 v141, 0xffff0000, v141
	v_and_b32_e32 v145, 0xffff0000, v145
	v_fma_f32 v16, v16, v204, v205
	v_fma_f32 v17, v17, v141, v145
	v_lshlrev_b32_e32 v204, 16, v142
	v_lshlrev_b32_e32 v205, 16, v146
	v_and_b32_e32 v142, 0xffff0000, v142
	v_and_b32_e32 v146, 0xffff0000, v146
	v_fma_f32 v10, v10, v204, v205
	v_fma_f32 v11, v11, v142, v146
	v_lshlrev_b32_e32 v204, 16, v143
	v_lshlrev_b32_e32 v205, 16, v147
	v_and_b32_e32 v143, 0xffff0000, v143
	v_and_b32_e32 v147, 0xffff0000, v147
	v_fma_f32 v12, v12, v204, v205
	v_fma_f32 v13, v13, v143, v147
	v_cvt_pk_bf16_f32 v140, v14, v15
	v_cvt_pk_bf16_f32 v141, v16, v17
	v_cvt_pk_bf16_f32 v142, v10, v11
	v_cvt_pk_bf16_f32 v143, v12, v13
	v_add_u32_e32 v207, 0x58000, v202
	global_store_dwordx4 v207, v[140:143], s[4:5]
	v_mul_f32_e32 v6, s80, v6
	v_mul_f32_e32 v7, s80, v7
	v_mul_f32_e32 v8, s80, v8
	v_mul_f32_e32 v9, s80, v9
	v_mul_f32_e32 v2, s80, v2
	v_mul_f32_e32 v3, s80, v3
	v_mul_f32_e32 v4, s80, v4
	v_mul_f32_e32 v5, s80, v5
	v_exp_f32_e32 v6, v6
	v_exp_f32_e32 v7, v7
	v_exp_f32_e32 v8, v8
	v_exp_f32_e32 v9, v9
	v_exp_f32_e32 v2, v2
	v_exp_f32_e32 v3, v3
	v_exp_f32_e32 v4, v4
	v_exp_f32_e32 v5, v5
	v_add_f32_e32 v6, 1.0, v6
	v_add_f32_e32 v7, 1.0, v7
	v_add_f32_e32 v8, 1.0, v8
	v_add_f32_e32 v9, 1.0, v9
	v_add_f32_e32 v2, 1.0, v2
	v_add_f32_e32 v3, 1.0, v3
	v_add_f32_e32 v4, 1.0, v4
	v_add_f32_e32 v5, 1.0, v5
	v_rcp_f32_e32 v6, v6
	v_rcp_f32_e32 v7, v7
	v_rcp_f32_e32 v8, v8
	v_rcp_f32_e32 v9, v9
	v_rcp_f32_e32 v2, v2
	v_rcp_f32_e32 v3, v3
	v_rcp_f32_e32 v4, v4
	v_rcp_f32_e32 v5, v5
	s_waitcnt vmcnt(6)
	v_lshlrev_b32_e32 v204, 16, v152
	v_lshlrev_b32_e32 v205, 16, v156
	v_and_b32_e32 v152, 0xffff0000, v152
	v_and_b32_e32 v156, 0xffff0000, v156
	v_fma_f32 v6, v6, v204, v205
	v_fma_f32 v7, v7, v152, v156
	v_lshlrev_b32_e32 v204, 16, v153
	v_lshlrev_b32_e32 v205, 16, v157
	v_and_b32_e32 v153, 0xffff0000, v153
	v_and_b32_e32 v157, 0xffff0000, v157
	v_fma_f32 v8, v8, v204, v205
	v_fma_f32 v9, v9, v153, v157
	v_lshlrev_b32_e32 v204, 16, v154
	v_lshlrev_b32_e32 v205, 16, v158
	v_and_b32_e32 v154, 0xffff0000, v154
	v_and_b32_e32 v158, 0xffff0000, v158
	v_fma_f32 v2, v2, v204, v205
	v_fma_f32 v3, v3, v154, v158
	v_lshlrev_b32_e32 v204, 16, v155
	v_lshlrev_b32_e32 v205, 16, v159
	v_and_b32_e32 v155, 0xffff0000, v155
	v_and_b32_e32 v159, 0xffff0000, v159
	v_fma_f32 v4, v4, v204, v205
	v_fma_f32 v5, v5, v155, v159
	v_cvt_pk_bf16_f32 v152, v6, v7
	v_cvt_pk_bf16_f32 v153, v8, v9
	v_cvt_pk_bf16_f32 v154, v2, v3
	v_cvt_pk_bf16_f32 v155, v4, v5
	v_add_u32_e32 v207, 0x58000, v202
	global_store_dwordx4 v207, v[152:155], s[4:5] offset:256
	s_branch .Lg3epi_done
; __device__ __forceinline__ float bflo(unsigned u) { return __uint_as_float(u << 16); }
; __device__ __forceinline__ float bfhi(unsigned u) { return __uint_as_float(u & 0xffff0000u); }
; __device__ __forceinline__ f32x2 sigm2(f32x2 v) { const f32x2 a = v * -1.4426950408889634f; f32x2 e; e.x = __builtin_amdgcn_exp2f(a.x); e.y = __builtin_amdgcn_exp2f(a.y); const f32x2 d = e + 1.0f; f32x2 r; r.x = __builtin_amdgcn_rcpf(d.x); r.y = __builtin_amdgcn_rcpf(d.y); return r; }
;     __device__ __forceinline__ void operator()(const pg8::f32x4 (&acc)[2][2][4][2], const Unit& u, int wr, int wc, int fr_, int fq_) const {
;     ...
;                 for (int bj = 0; bj < 2; ++bj) { const size_t off = (size_t)row * DM + col0 + bj * HALF;
;                     const u32x4 t = *(const u32x4*)(T + off); const u32x4 xb = *(const u32x4*)(XB + off);
;                     pg8::f32x4 x0 = {bflo(xb.x), bfhi(xb.x), bflo(xb.y), bfhi(xb.y)}, x1 = {bflo(xb.z), bfhi(xb.z), bflo(xb.w), bfhi(xb.w)};
;                     const pg8::f32x4 a0 = acc[ai][bj][m][0], a1 = acc[ai][bj][m][1];
;                     { const f32x2 s0 = sigm2((f32x2){a0[0], a0[1]}), s1 = sigm2((f32x2){a0[2], a0[3]}), s2 = sigm2((f32x2){a1[0], a1[1]}), s3 = sigm2((f32x2){a1[2], a1[3]});
;                       x0[0] += s0.x * bflo(t.x); x0[1] += s0.y * bfhi(t.x); x0[2] += s1.x * bflo(t.y); x0[3] += s1.y * bfhi(t.y);
;                       x1[0] += s2.x * bflo(t.z); x1[1] += s2.y * bfhi(t.z); x1[2] += s3.x * bflo(t.w); x1[3] += s3.y * bfhi(t.w); }
;                     if (f32out) { *(pg8::f32x4*)(Xo + off) = x0; *(pg8::f32x4*)(Xo + off + 4) = x1; }
.Lg3epi_f32:
	global_load_dwordx4 v[140:143], v202, s[6:7]
	global_load_dwordx4 v[144:147], v202, s[10:11]
	global_load_dwordx4 v[152:155], v202, s[6:7] offset:256
	global_load_dwordx4 v[156:159], v202, s[10:11] offset:256
	v_add_u32_e32 v203, 0x8000, v202
	global_load_dwordx4 v[160:163], v203, s[6:7]
	global_load_dwordx4 v[164:167], v203, s[10:11]
	v_add_u32_e32 v203, 0x8000, v202
	global_load_dwordx4 v[168:171], v203, s[6:7] offset:256
	global_load_dwordx4 v[172:175], v203, s[10:11] offset:256
	v_add_u32_e32 v203, 0x10000, v202
	global_load_dwordx4 v[176:179], v203, s[6:7]
	global_load_dwordx4 v[180:183], v203, s[10:11]
	v_add_u32_e32 v203, 0x10000, v202
	global_load_dwordx4 v[184:187], v203, s[6:7] offset:256
	global_load_dwordx4 v[188:191], v203, s[10:11] offset:256
	v_add_u32_e32 v203, 0x18000, v202
	global_load_dwordx4 v[192:195], v203, s[6:7]
	global_load_dwordx4 v[196:199], v203, s[10:11]
	v_mul_f32_e32 v126, s80, v126
	v_mul_f32_e32 v127, s80, v127
	v_mul_f32_e32 v128, s80, v128
	v_mul_f32_e32 v129, s80, v129
	v_mul_f32_e32 v122, s80, v122
	v_mul_f32_e32 v123, s80, v123
	v_mul_f32_e32 v124, s80, v124
	v_mul_f32_e32 v125, s80, v125
	v_exp_f32_e32 v126, v126
	v_exp_f32_e32 v127, v127
	v_exp_f32_e32 v128, v128
	v_exp_f32_e32 v129, v129
	v_exp_f32_e32 v122, v122
	v_exp_f32_e32 v123, v123
	v_exp_f32_e32 v124, v124
	v_exp_f32_e32 v125, v125
	v_add_f32_e32 v126, 1.0, v126
	v_add_f32_e32 v127, 1.0, v127
	v_add_f32_e32 v128, 1.0, v128
	v_add_f32_e32 v129, 1.0, v129
	v_add_f32_e32 v122, 1.0, v122
	v_add_f32_e32 v123, 1.0, v123
	v_add_f32_e32 v124, 1.0, v124
	v_add_f32_e32 v125, 1.0, v125
	v_rcp_f32_e32 v126, v126
	v_rcp_f32_e32 v127, v127
	v_rcp_f32_e32 v128, v128
	v_rcp_f32_e32 v129, v129
	v_rcp_f32_e32 v122, v122
	v_rcp_f32_e32 v123, v123
	v_rcp_f32_e32 v124, v124
	v_rcp_f32_e32 v125, v125
	s_waitcnt vmcnt(12)
	v_lshlrev_b32_e32 v204, 16, v140
	v_lshlrev_b32_e32 v205, 16, v144
	v_and_b32_e32 v140, 0xffff0000, v140
	v_and_b32_e32 v144, 0xffff0000, v144
	v_fma_f32 v126, v126, v204, v205
	v_fma_f32 v127, v127, v140, v144
	v_lshlrev_b32_e32 v204, 16, v141
	v_lshlrev_b32_e32 v205, 16, v145
	v_and_b32_e32 v141, 0xffff0000, v141
	v_and_b32_e32 v145, 0xffff0000, v145
	v_fma_f32 v128, v128, v204, v205
	v_fma_f32 v129, v129, v141, v145
	v_lshlrev_b32_e32 v204, 16, v142
	v_lshlrev_b32_e32 v205, 16, v146
	v_and_b32_e32 v142, 0xffff0000, v142
	v_and_b32_e32 v146, 0xffff0000, v146
	v_fma_f32 v122, v122, v204, v205
	v_fma_f32 v123, v123, v142, v146
	v_lshlrev_b32_e32 v204, 16, v143
	v_lshlrev_b32_e32 v205, 16, v147
	v_and_b32_e32 v143, 0xffff0000, v143
	v_and_b32_e32 v147, 0xffff0000, v147
	v_fma_f32 v124, v124, v204, v205
	v_fma_f32 v125, v125, v143, v147
	global_store_dwordx4 v206, v[126:129], s[4:5]
	global_store_dwordx4 v206, v[122:125], s[4:5] offset:16
	v_add_u32_e32 v203, 0x18000, v202
	global_load_dwordx4 v[140:143], v203, s[6:7] offset:256
	global_load_dwordx4 v[144:147], v203, s[10:11] offset:256
	v_mul_f32_e32 v118, s80, v118
	v_mul_f32_e32 v119, s80, v119
	v_mul_f32_e32 v120, s80, v120
	v_mul_f32_e32 v121, s80, v121
	v_mul_f32_e32 v114, s80, v114
	v_mul_f32_e32 v115, s80, v115
	v_mul_f32_e32 v116, s80, v116
	v_mul_f32_e32 v117, s80, v117
	v_exp_f32_e32 v118, v118
	v_exp_f32_e32 v119, v119
	v_exp_f32_e32 v120, v120
	v_exp_f32_e32 v121, v121
	v_exp_f32_e32 v114, v114
	v_exp_f32_e32 v115, v115
	v_exp_f32_e32 v116, v116
	v_exp_f32_e32 v117, v117
	v_add_f32_e32 v118, 1.0, v118
	v_add_f32_e32 v119, 1.0, v119
	v_add_f32_e32 v120, 1.0, v120
	v_add_f32_e32 v121, 1.0, v121
	v_add_f32_e32 v114, 1.0, v114
	v_add_f32_e32 v115, 1.0, v115
	v_add_f32_e32 v116, 1.0, v116
	v_add_f32_e32 v117, 1.0, v117
	v_rcp_f32_e32 v118, v118
	v_rcp_f32_e32 v119, v119
	v_rcp_f32_e32 v120, v120
	v_rcp_f32_e32 v121, v121
	v_rcp_f32_e32 v114, v114
	v_rcp_f32_e32 v115, v115
	v_rcp_f32_e32 v116, v116
	v_rcp_f32_e32 v117, v117
	s_waitcnt vmcnt(14)
	v_lshlrev_b32_e32 v204, 16, v152
	v_lshlrev_b32_e32 v205, 16, v156
	v_and_b32_e32 v152, 0xffff0000, v152
	v_and_b32_e32 v156, 0xffff0000, v156
	v_fma_f32 v118, v118, v204, v205
	v_fma_f32 v119, v119, v152, v156
	v_lshlrev_b32_e32 v204, 16, v153
	v_lshlrev_b32_e32 v205, 16, v157
	v_and_b32_e32 v153, 0xffff0000, v153
	v_and_b32_e32 v157, 0xffff0000, v157
	v_fma_f32 v120, v120, v204, v205
	v_fma_f32 v121, v121, v153, v157
	v_lshlrev_b32_e32 v204, 16, v154
	v_lshlrev_b32_e32 v205, 16, v158
	v_and_b32_e32 v154, 0xffff0000, v154
	v_and_b32_e32 v158, 0xffff0000, v158
	v_fma_f32 v114, v114, v204, v205
	v_fma_f32 v115, v115, v154, v158
	v_lshlrev_b32_e32 v204, 16, v155
	v_lshlrev_b32_e32 v205, 16, v159
	v_and_b32_e32 v155, 0xffff0000, v155
	v_and_b32_e32 v159, 0xffff0000, v159
	v_fma_f32 v116, v116, v204, v205
	v_fma_f32 v117, v117, v155, v159
	global_store_dwordx4 v206, v[118:121], s[4:5] offset:512
	global_store_dwordx4 v206, v[114:117], s[4:5] offset:528
	v_add_u32_e32 v203, 0x40000, v202
	global_load_dwordx4 v[152:155], v203, s[6:7]
	global_load_dwordx4 v[156:159], v203, s[10:11]
	v_mul_f32_e32 v110, s80, v110
	v_mul_f32_e32 v111, s80, v111
	v_mul_f32_e32 v112, s80, v112
	v_mul_f32_e32 v113, s80, v113
	v_mul_f32_e32 v106, s80, v106
	v_mul_f32_e32 v107, s80, v107
	v_mul_f32_e32 v108, s80, v108
	v_mul_f32_e32 v109, s80, v109
	v_exp_f32_e32 v110, v110
	v_exp_f32_e32 v111, v111
	v_exp_f32_e32 v112, v112
	v_exp_f32_e32 v113, v113
	v_exp_f32_e32 v106, v106
	v_exp_f32_e32 v107, v107
	v_exp_f32_e32 v108, v108
	v_exp_f32_e32 v109, v109
	v_add_f32_e32 v110, 1.0, v110
	v_add_f32_e32 v111, 1.0, v111
	v_add_f32_e32 v112, 1.0, v112
	v_add_f32_e32 v113, 1.0, v113
	v_add_f32_e32 v106, 1.0, v106
	v_add_f32_e32 v107, 1.0, v107
	v_add_f32_e32 v108, 1.0, v108
	v_add_f32_e32 v109, 1.0, v109
	v_rcp_f32_e32 v110, v110
	v_rcp_f32_e32 v111, v111
	v_rcp_f32_e32 v112, v112
	v_rcp_f32_e32 v113, v113
	v_rcp_f32_e32 v106, v106
	v_rcp_f32_e32 v107, v107
	v_rcp_f32_e32 v108, v108
	v_rcp_f32_e32 v109, v109
	s_waitcnt vmcnt(16)
; __device__ __forceinline__ float bflo(unsigned u) { return __uint_as_float(u << 16); }
; __device__ __forceinline__ float bfhi(unsigned u) { return __uint_as_float(u & 0xffff0000u); }
; __device__ __forceinline__ f32x2 sigm2(f32x2 v) { const f32x2 a = v * -1.4426950408889634f; f32x2 e; e.x = __builtin_amdgcn_exp2f(a.x); e.y = __builtin_amdgcn_exp2f(a.y); const f32x2 d = e + 1.0f; f32x2 r; r.x = __builtin_amdgcn_rcpf(d.x); r.y = __builtin_amdgcn_rcpf(d.y); return r; }
;     __device__ __forceinline__ void operator()(const pg8::f32x4 (&acc)[2][2][4][2], const Unit& u, int wr, int wc, int fr_, int fq_) const {
;     ...
;                 for (int bj = 0; bj < 2; ++bj) { const size_t off = (size_t)row * DM + col0 + bj * HALF;
;                     const u32x4 t = *(const u32x4*)(T + off); const u32x4 xb = *(const u32x4*)(XB + off);
;                     pg8::f32x4 x0 = {bflo(xb.x), bfhi(xb.x), bflo(xb.y), bfhi(xb.y)}, x1 = {bflo(xb.z), bfhi(xb.z), bflo(xb.w), bfhi(xb.w)};
;                     const pg8::f32x4 a0 = acc[ai][bj][m][0], a1 = acc[ai][bj][m][1];
;                     { const f32x2 s0 = sigm2((f32x2){a0[0], a0[1]}), s1 = sigm2((f32x2){a0[2], a0[3]}), s2 = sigm2((f32x2){a1[0], a1[1]}), s3 = sigm2((f32x2){a1[2], a1[3]});
;                       x0[0] += s0.x * bflo(t.x); x0[1] += s0.y * bfhi(t.x); x0[2] += s1.x * bflo(t.y); x0[3] += s1.y * bfhi(t.y);
;                       x1[0] += s2.x * bflo(t.z); x1[1] += s2.y * bfhi(t.z); x1[2] += s3.x * bflo(t.w); x1[3] += s3.y * bfhi(t.w); }
;                     if (f32out) { *(pg8::f32x4*)(Xo + off) = x0; *(pg8::f32x4*)(Xo + off + 4) = x1; }
	v_lshlrev_b32_e32 v204, 16, v160
	v_lshlrev_b32_e32 v205, 16, v164
	v_and_b32_e32 v160, 0xffff0000, v160
	v_and_b32_e32 v164, 0xffff0000, v164
	v_fma_f32 v110, v110, v204, v205
	v_fma_f32 v111, v111, v160, v164
	v_lshlrev_b32_e32 v204, 16, v161
	v_lshlrev_b32_e32 v205, 16, v165
	v_and_b32_e32 v161, 0xffff0000, v161
	v_and_b32_e32 v165, 0xffff0000, v165
	v_fma_f32 v112, v112, v204, v205
	v_fma_f32 v113, v113, v161, v165
	v_lshlrev_b32_e32 v204, 16, v162
	v_lshlrev_b32_e32 v205, 16, v166
	v_and_b32_e32 v162, 0xffff0000, v162
	v_and_b32_e32 v166, 0xffff0000, v166
	v_fma_f32 v106, v106, v204, v205
	v_fma_f32 v107, v107, v162, v166
	v_lshlrev_b32_e32 v204, 16, v163
	v_lshlrev_b32_e32 v205, 16, v167
	v_and_b32_e32 v163, 0xffff0000, v163
	v_and_b32_e32 v167, 0xffff0000, v167
	v_fma_f32 v108, v108, v204, v205
	v_fma_f32 v109, v109, v163, v167
	v_add_u32_e32 v207, 0x10000, v206
	global_store_dwordx4 v207, v[110:113], s[4:5]
	global_store_dwordx4 v207, v[106:109], s[4:5] offset:16
	v_add_u32_e32 v203, 0x40000, v202
	global_load_dwordx4 v[160:163], v203, s[6:7] offset:256
	global_load_dwordx4 v[164:167], v203, s[10:11] offset:256
	v_mul_f32_e32 v102, s80, v102
	v_mul_f32_e32 v103, s80, v103
	v_mul_f32_e32 v104, s80, v104
	v_mul_f32_e32 v105, s80, v105
	v_mul_f32_e32 v98, s80, v98
	v_mul_f32_e32 v99, s80, v99
	v_mul_f32_e32 v100, s80, v100
	v_mul_f32_e32 v101, s80, v101
	v_exp_f32_e32 v102, v102
	v_exp_f32_e32 v103, v103
	v_exp_f32_e32 v104, v104
	v_exp_f32_e32 v105, v105
	v_exp_f32_e32 v98, v98
	v_exp_f32_e32 v99, v99
	v_exp_f32_e32 v100, v100
	v_exp_f32_e32 v101, v101
	v_add_f32_e32 v102, 1.0, v102
	v_add_f32_e32 v103, 1.0, v103
	v_add_f32_e32 v104, 1.0, v104
	v_add_f32_e32 v105, 1.0, v105
	v_add_f32_e32 v98, 1.0, v98
	v_add_f32_e32 v99, 1.0, v99
	v_add_f32_e32 v100, 1.0, v100
	v_add_f32_e32 v101, 1.0, v101
	v_rcp_f32_e32 v102, v102
	v_rcp_f32_e32 v103, v103
	v_rcp_f32_e32 v104, v104
	v_rcp_f32_e32 v105, v105
	v_rcp_f32_e32 v98, v98
	v_rcp_f32_e32 v99, v99
	v_rcp_f32_e32 v100, v100
	v_rcp_f32_e32 v101, v101
	s_waitcnt vmcnt(18)
	v_lshlrev_b32_e32 v204, 16, v168
	v_lshlrev_b32_e32 v205, 16, v172
	v_and_b32_e32 v168, 0xffff0000, v168
	v_and_b32_e32 v172, 0xffff0000, v172
	v_fma_f32 v102, v102, v204, v205
	v_fma_f32 v103, v103, v168, v172
	v_lshlrev_b32_e32 v204, 16, v169
	v_lshlrev_b32_e32 v205, 16, v173
	v_and_b32_e32 v169, 0xffff0000, v169
	v_and_b32_e32 v173, 0xffff0000, v173
	v_fma_f32 v104, v104, v204, v205
	v_fma_f32 v105, v105, v169, v173
	v_lshlrev_b32_e32 v204, 16, v170
	v_lshlrev_b32_e32 v205, 16, v174
	v_and_b32_e32 v170, 0xffff0000, v170
	v_and_b32_e32 v174, 0xffff0000, v174
	v_fma_f32 v98, v98, v204, v205
	v_fma_f32 v99, v99, v170, v174
	v_lshlrev_b32_e32 v204, 16, v171
	v_lshlrev_b32_e32 v205, 16, v175
	v_and_b32_e32 v171, 0xffff0000, v171
	v_and_b32_e32 v175, 0xffff0000, v175
	v_fma_f32 v100, v100, v204, v205
	v_fma_f32 v101, v101, v171, v175
	v_add_u32_e32 v207, 0x10000, v206
	global_store_dwordx4 v207, v[102:105], s[4:5] offset:512
	global_store_dwordx4 v207, v[98:101], s[4:5] offset:528
	v_add_u32_e32 v203, 0x48000, v202
	global_load_dwordx4 v[168:171], v203, s[6:7]
	global_load_dwordx4 v[172:175], v203, s[10:11]
	v_mul_f32_e32 v94, s80, v94
	v_mul_f32_e32 v95, s80, v95
	v_mul_f32_e32 v96, s80, v96
	v_mul_f32_e32 v97, s80, v97
	v_mul_f32_e32 v90, s80, v90
	v_mul_f32_e32 v91, s80, v91
	v_mul_f32_e32 v92, s80, v92
	v_mul_f32_e32 v93, s80, v93
	v_exp_f32_e32 v94, v94
	v_exp_f32_e32 v95, v95
	v_exp_f32_e32 v96, v96
	v_exp_f32_e32 v97, v97
	v_exp_f32_e32 v90, v90
	v_exp_f32_e32 v91, v91
	v_exp_f32_e32 v92, v92
	v_exp_f32_e32 v93, v93
	v_add_f32_e32 v94, 1.0, v94
	v_add_f32_e32 v95, 1.0, v95
	v_add_f32_e32 v96, 1.0, v96
	v_add_f32_e32 v97, 1.0, v97
	v_add_f32_e32 v90, 1.0, v90
	v_add_f32_e32 v91, 1.0, v91
	v_add_f32_e32 v92, 1.0, v92
	v_add_f32_e32 v93, 1.0, v93
	v_rcp_f32_e32 v94, v94
	v_rcp_f32_e32 v95, v95
	v_rcp_f32_e32 v96, v96
	v_rcp_f32_e32 v97, v97
	v_rcp_f32_e32 v90, v90
	v_rcp_f32_e32 v91, v91
	v_rcp_f32_e32 v92, v92
	v_rcp_f32_e32 v93, v93
	s_waitcnt vmcnt(20)
	v_lshlrev_b32_e32 v204, 16, v176
	v_lshlrev_b32_e32 v205, 16, v180
	v_and_b32_e32 v176, 0xffff0000, v176
	v_and_b32_e32 v180, 0xffff0000, v180
	v_fma_f32 v94, v94, v204, v205
	v_fma_f32 v95, v95, v176, v180
	v_lshlrev_b32_e32 v204, 16, v177
	v_lshlrev_b32_e32 v205, 16, v181
	v_and_b32_e32 v177, 0xffff0000, v177
	v_and_b32_e32 v181, 0xffff0000, v181
	v_fma_f32 v96, v96, v204, v205
	v_fma_f32 v97, v97, v177, v181
	v_lshlrev_b32_e32 v204, 16, v178
	v_lshlrev_b32_e32 v205, 16, v182
	v_and_b32_e32 v178, 0xffff0000, v178
	v_and_b32_e32 v182, 0xffff0000, v182
	v_fma_f32 v90, v90, v204, v205
	v_fma_f32 v91, v91, v178, v182
	v_lshlrev_b32_e32 v204, 16, v179
	v_lshlrev_b32_e32 v205, 16, v183
	v_and_b32_e32 v179, 0xffff0000, v179
	v_and_b32_e32 v183, 0xffff0000, v183
	v_fma_f32 v92, v92, v204, v205
	v_fma_f32 v93, v93, v179, v183
	v_add_u32_e32 v207, 0x20000, v206
	global_store_dwordx4 v207, v[94:97], s[4:5]
	global_store_dwordx4 v207, v[90:93], s[4:5] offset:16
	v_add_u32_e32 v203, 0x48000, v202
	global_load_dwordx4 v[176:179], v203, s[6:7] offset:256
	global_load_dwordx4 v[180:183], v203, s[10:11] offset:256
	v_mul_f32_e32 v86, s80, v86
	v_mul_f32_e32 v87, s80, v87
	v_mul_f32_e32 v88, s80, v88
	v_mul_f32_e32 v89, s80, v89
	v_mul_f32_e32 v82, s80, v82
	v_mul_f32_e32 v83, s80, v83
	v_mul_f32_e32 v84, s80, v84
	v_mul_f32_e32 v85, s80, v85
	v_exp_f32_e32 v86, v86
	v_exp_f32_e32 v87, v87
	v_exp_f32_e32 v88, v88
	v_exp_f32_e32 v89, v89
	v_exp_f32_e32 v82, v82
	v_exp_f32_e32 v83, v83
	v_exp_f32_e32 v84, v84
	v_exp_f32_e32 v85, v85
	v_add_f32_e32 v86, 1.0, v86
	v_add_f32_e32 v87, 1.0, v87
	v_add_f32_e32 v88, 1.0, v88
	v_add_f32_e32 v89, 1.0, v89
	v_add_f32_e32 v82, 1.0, v82
	v_add_f32_e32 v83, 1.0, v83
	v_add_f32_e32 v84, 1.0, v84
	v_add_f32_e32 v85, 1.0, v85
	v_rcp_f32_e32 v86, v86
	v_rcp_f32_e32 v87, v87
	v_rcp_f32_e32 v88, v88
	v_rcp_f32_e32 v89, v89
	v_rcp_f32_e32 v82, v82
	v_rcp_f32_e32 v83, v83
	v_rcp_f32_e32 v84, v84
	v_rcp_f32_e32 v85, v85
	s_waitcnt vmcnt(22)
; __device__ __forceinline__ float bflo(unsigned u) { return __uint_as_float(u << 16); }
; __device__ __forceinline__ float bfhi(unsigned u) { return __uint_as_float(u & 0xffff0000u); }
; __device__ __forceinline__ f32x2 sigm2(f32x2 v) { const f32x2 a = v * -1.4426950408889634f; f32x2 e; e.x = __builtin_amdgcn_exp2f(a.x); e.y = __builtin_amdgcn_exp2f(a.y); const f32x2 d = e + 1.0f; f32x2 r; r.x = __builtin_amdgcn_rcpf(d.x); r.y = __builtin_amdgcn_rcpf(d.y); return r; }
;     __device__ __forceinline__ void operator()(const pg8::f32x4 (&acc)[2][2][4][2], const Unit& u, int wr, int wc, int fr_, int fq_) const {
;     ...
;                 for (int bj = 0; bj < 2; ++bj) { const size_t off = (size_t)row * DM + col0 + bj * HALF;
;                     const u32x4 t = *(const u32x4*)(T + off); const u32x4 xb = *(const u32x4*)(XB + off);
;                     pg8::f32x4 x0 = {bflo(xb.x), bfhi(xb.x), bflo(xb.y), bfhi(xb.y)}, x1 = {bflo(xb.z), bfhi(xb.z), bflo(xb.w), bfhi(xb.w)};
;                     const pg8::f32x4 a0 = acc[ai][bj][m][0], a1 = acc[ai][bj][m][1];
;                     { const f32x2 s0 = sigm2((f32x2){a0[0], a0[1]}), s1 = sigm2((f32x2){a0[2], a0[3]}), s2 = sigm2((f32x2){a1[0], a1[1]}), s3 = sigm2((f32x2){a1[2], a1[3]});
;                       x0[0] += s0.x * bflo(t.x); x0[1] += s0.y * bfhi(t.x); x0[2] += s1.x * bflo(t.y); x0[3] += s1.y * bfhi(t.y);
;                       x1[0] += s2.x * bflo(t.z); x1[1] += s2.y * bfhi(t.z); x1[2] += s3.x * bflo(t.w); x1[3] += s3.y * bfhi(t.w); }
;                     if (f32out) { *(pg8::f32x4*)(Xo + off) = x0; *(pg8::f32x4*)(Xo + off + 4) = x1; }
	v_lshlrev_b32_e32 v204, 16, v184
	v_lshlrev_b32_e32 v205, 16, v188
	v_and_b32_e32 v184, 0xffff0000, v184
	v_and_b32_e32 v188, 0xffff0000, v188
	v_fma_f32 v86, v86, v204, v205
	v_fma_f32 v87, v87, v184, v188
	v_lshlrev_b32_e32 v204, 16, v185
	v_lshlrev_b32_e32 v205, 16, v189
	v_and_b32_e32 v185, 0xffff0000, v185
	v_and_b32_e32 v189, 0xffff0000, v189
	v_fma_f32 v88, v88, v204, v205
	v_fma_f32 v89, v89, v185, v189
	v_lshlrev_b32_e32 v204, 16, v186
	v_lshlrev_b32_e32 v205, 16, v190
	v_and_b32_e32 v186, 0xffff0000, v186
	v_and_b32_e32 v190, 0xffff0000, v190
	v_fma_f32 v82, v82, v204, v205
	v_fma_f32 v83, v83, v186, v190
	v_lshlrev_b32_e32 v204, 16, v187
	v_lshlrev_b32_e32 v205, 16, v191
	v_and_b32_e32 v187, 0xffff0000, v187
	v_and_b32_e32 v191, 0xffff0000, v191
	v_fma_f32 v84, v84, v204, v205
	v_fma_f32 v85, v85, v187, v191
	v_add_u32_e32 v207, 0x20000, v206
	global_store_dwordx4 v207, v[86:89], s[4:5] offset:512
	global_store_dwordx4 v207, v[82:85], s[4:5] offset:528
	v_add_u32_e32 v203, 0x50000, v202
	global_load_dwordx4 v[184:187], v203, s[6:7]
	global_load_dwordx4 v[188:191], v203, s[10:11]
	v_mul_f32_e32 v78, s80, v78
	v_mul_f32_e32 v79, s80, v79
	v_mul_f32_e32 v80, s80, v80
	v_mul_f32_e32 v81, s80, v81
	v_mul_f32_e32 v74, s80, v74
	v_mul_f32_e32 v75, s80, v75
	v_mul_f32_e32 v76, s80, v76
	v_mul_f32_e32 v77, s80, v77
	v_exp_f32_e32 v78, v78
	v_exp_f32_e32 v79, v79
	v_exp_f32_e32 v80, v80
	v_exp_f32_e32 v81, v81
	v_exp_f32_e32 v74, v74
	v_exp_f32_e32 v75, v75
	v_exp_f32_e32 v76, v76
	v_exp_f32_e32 v77, v77
	v_add_f32_e32 v78, 1.0, v78
	v_add_f32_e32 v79, 1.0, v79
	v_add_f32_e32 v80, 1.0, v80
	v_add_f32_e32 v81, 1.0, v81
	v_add_f32_e32 v74, 1.0, v74
	v_add_f32_e32 v75, 1.0, v75
	v_add_f32_e32 v76, 1.0, v76
	v_add_f32_e32 v77, 1.0, v77
	v_rcp_f32_e32 v78, v78
	v_rcp_f32_e32 v79, v79
	v_rcp_f32_e32 v80, v80
	v_rcp_f32_e32 v81, v81
	v_rcp_f32_e32 v74, v74
	v_rcp_f32_e32 v75, v75
	v_rcp_f32_e32 v76, v76
	v_rcp_f32_e32 v77, v77
	s_waitcnt vmcnt(24)
	v_lshlrev_b32_e32 v204, 16, v192
	v_lshlrev_b32_e32 v205, 16, v196
	v_and_b32_e32 v192, 0xffff0000, v192
	v_and_b32_e32 v196, 0xffff0000, v196
	v_fma_f32 v78, v78, v204, v205
	v_fma_f32 v79, v79, v192, v196
	v_lshlrev_b32_e32 v204, 16, v193
	v_lshlrev_b32_e32 v205, 16, v197
	v_and_b32_e32 v193, 0xffff0000, v193
	v_and_b32_e32 v197, 0xffff0000, v197
	v_fma_f32 v80, v80, v204, v205
	v_fma_f32 v81, v81, v193, v197
	v_lshlrev_b32_e32 v204, 16, v194
	v_lshlrev_b32_e32 v205, 16, v198
	v_and_b32_e32 v194, 0xffff0000, v194
	v_and_b32_e32 v198, 0xffff0000, v198
	v_fma_f32 v74, v74, v204, v205
	v_fma_f32 v75, v75, v194, v198
	v_lshlrev_b32_e32 v204, 16, v195
	v_lshlrev_b32_e32 v205, 16, v199
	v_and_b32_e32 v195, 0xffff0000, v195
	v_and_b32_e32 v199, 0xffff0000, v199
	v_fma_f32 v76, v76, v204, v205
	v_fma_f32 v77, v77, v195, v199
	v_add_u32_e32 v207, 0x30000, v206
	global_store_dwordx4 v207, v[78:81], s[4:5]
	global_store_dwordx4 v207, v[74:77], s[4:5] offset:16
	v_add_u32_e32 v203, 0x50000, v202
	global_load_dwordx4 v[192:195], v203, s[6:7] offset:256
	global_load_dwordx4 v[196:199], v203, s[10:11] offset:256
	v_mul_f32_e32 v70, s80, v70
	v_mul_f32_e32 v71, s80, v71
	v_mul_f32_e32 v72, s80, v72
	v_mul_f32_e32 v73, s80, v73
	v_mul_f32_e32 v66, s80, v66
	v_mul_f32_e32 v67, s80, v67
	v_mul_f32_e32 v68, s80, v68
	v_mul_f32_e32 v69, s80, v69
	v_exp_f32_e32 v70, v70
	v_exp_f32_e32 v71, v71
	v_exp_f32_e32 v72, v72
	v_exp_f32_e32 v73, v73
	v_exp_f32_e32 v66, v66
	v_exp_f32_e32 v67, v67
	v_exp_f32_e32 v68, v68
	v_exp_f32_e32 v69, v69
	v_add_f32_e32 v70, 1.0, v70
	v_add_f32_e32 v71, 1.0, v71
	v_add_f32_e32 v72, 1.0, v72
	v_add_f32_e32 v73, 1.0, v73
	v_add_f32_e32 v66, 1.0, v66
	v_add_f32_e32 v67, 1.0, v67
	v_add_f32_e32 v68, 1.0, v68
	v_add_f32_e32 v69, 1.0, v69
	v_rcp_f32_e32 v70, v70
	v_rcp_f32_e32 v71, v71
	v_rcp_f32_e32 v72, v72
	v_rcp_f32_e32 v73, v73
	v_rcp_f32_e32 v66, v66
	v_rcp_f32_e32 v67, v67
	v_rcp_f32_e32 v68, v68
	v_rcp_f32_e32 v69, v69
	s_waitcnt vmcnt(24)
	v_lshlrev_b32_e32 v204, 16, v140
	v_lshlrev_b32_e32 v205, 16, v144
	v_and_b32_e32 v140, 0xffff0000, v140
	v_and_b32_e32 v144, 0xffff0000, v144
	v_fma_f32 v70, v70, v204, v205
	v_fma_f32 v71, v71, v140, v144
	v_lshlrev_b32_e32 v204, 16, v141
	v_lshlrev_b32_e32 v205, 16, v145
	v_and_b32_e32 v141, 0xffff0000, v141
	v_and_b32_e32 v145, 0xffff0000, v145
	v_fma_f32 v72, v72, v204, v205
	v_fma_f32 v73, v73, v141, v145
	v_lshlrev_b32_e32 v204, 16, v142
	v_lshlrev_b32_e32 v205, 16, v146
	v_and_b32_e32 v142, 0xffff0000, v142
	v_and_b32_e32 v146, 0xffff0000, v146
	v_fma_f32 v66, v66, v204, v205
	v_fma_f32 v67, v67, v142, v146
	v_lshlrev_b32_e32 v204, 16, v143
	v_lshlrev_b32_e32 v205, 16, v147
	v_and_b32_e32 v143, 0xffff0000, v143
	v_and_b32_e32 v147, 0xffff0000, v147
	v_fma_f32 v68, v68, v204, v205
	v_fma_f32 v69, v69, v143, v147
	v_add_u32_e32 v207, 0x30000, v206
	global_store_dwordx4 v207, v[70:73], s[4:5] offset:512
	global_store_dwordx4 v207, v[66:69], s[4:5] offset:528
	v_add_u32_e32 v203, 0x58000, v202
	global_load_dwordx4 v[140:143], v203, s[6:7]
	global_load_dwordx4 v[144:147], v203, s[10:11]
	v_mul_f32_e32 v62, s80, v62
	v_mul_f32_e32 v63, s80, v63
	v_mul_f32_e32 v64, s80, v64
	v_mul_f32_e32 v65, s80, v65
	v_mul_f32_e32 v58, s80, v58
	v_mul_f32_e32 v59, s80, v59
	v_mul_f32_e32 v60, s80, v60
	v_mul_f32_e32 v61, s80, v61
	v_exp_f32_e32 v62, v62
	v_exp_f32_e32 v63, v63
	v_exp_f32_e32 v64, v64
	v_exp_f32_e32 v65, v65
	v_exp_f32_e32 v58, v58
	v_exp_f32_e32 v59, v59
	v_exp_f32_e32 v60, v60
	v_exp_f32_e32 v61, v61
	v_add_f32_e32 v62, 1.0, v62
	v_add_f32_e32 v63, 1.0, v63
	v_add_f32_e32 v64, 1.0, v64
	v_add_f32_e32 v65, 1.0, v65
	v_add_f32_e32 v58, 1.0, v58
	v_add_f32_e32 v59, 1.0, v59
	v_add_f32_e32 v60, 1.0, v60
	v_add_f32_e32 v61, 1.0, v61
	v_rcp_f32_e32 v62, v62
	v_rcp_f32_e32 v63, v63
	v_rcp_f32_e32 v64, v64
	v_rcp_f32_e32 v65, v65
	v_rcp_f32_e32 v58, v58
	v_rcp_f32_e32 v59, v59
	v_rcp_f32_e32 v60, v60
	v_rcp_f32_e32 v61, v61
	s_waitcnt vmcnt(24)
; __device__ __forceinline__ float bflo(unsigned u) { return __uint_as_float(u << 16); }
; __device__ __forceinline__ float bfhi(unsigned u) { return __uint_as_float(u & 0xffff0000u); }
; __device__ __forceinline__ f32x2 sigm2(f32x2 v) { const f32x2 a = v * -1.4426950408889634f; f32x2 e; e.x = __builtin_amdgcn_exp2f(a.x); e.y = __builtin_amdgcn_exp2f(a.y); const f32x2 d = e + 1.0f; f32x2 r; r.x = __builtin_amdgcn_rcpf(d.x); r.y = __builtin_amdgcn_rcpf(d.y); return r; }
;     __device__ __forceinline__ void operator()(const pg8::f32x4 (&acc)[2][2][4][2], const Unit& u, int wr, int wc, int fr_, int fq_) const {
;     ...
;                 for (int bj = 0; bj < 2; ++bj) { const size_t off = (size_t)row * DM + col0 + bj * HALF;
;                     const u32x4 t = *(const u32x4*)(T + off); const u32x4 xb = *(const u32x4*)(XB + off);
;                     pg8::f32x4 x0 = {bflo(xb.x), bfhi(xb.x), bflo(xb.y), bfhi(xb.y)}, x1 = {bflo(xb.z), bfhi(xb.z), bflo(xb.w), bfhi(xb.w)};
;                     const pg8::f32x4 a0 = acc[ai][bj][m][0], a1 = acc[ai][bj][m][1];
;                     { const f32x2 s0 = sigm2((f32x2){a0[0], a0[1]}), s1 = sigm2((f32x2){a0[2], a0[3]}), s2 = sigm2((f32x2){a1[0], a1[1]}), s3 = sigm2((f32x2){a1[2], a1[3]});
;                       x0[0] += s0.x * bflo(t.x); x0[1] += s0.y * bfhi(t.x); x0[2] += s1.x * bflo(t.y); x0[3] += s1.y * bfhi(t.y);
;                       x1[0] += s2.x * bflo(t.z); x1[1] += s2.y * bfhi(t.z); x1[2] += s3.x * bflo(t.w); x1[3] += s3.y * bfhi(t.w); }
;                     if (f32out) { *(pg8::f32x4*)(Xo + off) = x0; *(pg8::f32x4*)(Xo + off + 4) = x1; }
	v_lshlrev_b32_e32 v204, 16, v152
	v_lshlrev_b32_e32 v205, 16, v156
	v_and_b32_e32 v152, 0xffff0000, v152
	v_and_b32_e32 v156, 0xffff0000, v156
	v_fma_f32 v62, v62, v204, v205
	v_fma_f32 v63, v63, v152, v156
	v_lshlrev_b32_e32 v204, 16, v153
	v_lshlrev_b32_e32 v205, 16, v157
	v_and_b32_e32 v153, 0xffff0000, v153
	v_and_b32_e32 v157, 0xffff0000, v157
	v_fma_f32 v64, v64, v204, v205
	v_fma_f32 v65, v65, v153, v157
	v_lshlrev_b32_e32 v204, 16, v154
	v_lshlrev_b32_e32 v205, 16, v158
	v_and_b32_e32 v154, 0xffff0000, v154
	v_and_b32_e32 v158, 0xffff0000, v158
	v_fma_f32 v58, v58, v204, v205
	v_fma_f32 v59, v59, v154, v158
	v_lshlrev_b32_e32 v204, 16, v155
	v_lshlrev_b32_e32 v205, 16, v159
	v_and_b32_e32 v155, 0xffff0000, v155
	v_and_b32_e32 v159, 0xffff0000, v159
	v_fma_f32 v60, v60, v204, v205
	v_fma_f32 v61, v61, v155, v159
	v_add_u32_e32 v207, 0x80000, v206
	global_store_dwordx4 v207, v[62:65], s[4:5]
	global_store_dwordx4 v207, v[58:61], s[4:5] offset:16
	v_add_u32_e32 v203, 0x58000, v202
	global_load_dwordx4 v[152:155], v203, s[6:7] offset:256
	global_load_dwordx4 v[156:159], v203, s[10:11] offset:256
	v_mul_f32_e32 v54, s80, v54
	v_mul_f32_e32 v55, s80, v55
	v_mul_f32_e32 v56, s80, v56
	v_mul_f32_e32 v57, s80, v57
	v_mul_f32_e32 v50, s80, v50
	v_mul_f32_e32 v51, s80, v51
	v_mul_f32_e32 v52, s80, v52
	v_mul_f32_e32 v53, s80, v53
	v_exp_f32_e32 v54, v54
	v_exp_f32_e32 v55, v55
	v_exp_f32_e32 v56, v56
	v_exp_f32_e32 v57, v57
	v_exp_f32_e32 v50, v50
	v_exp_f32_e32 v51, v51
	v_exp_f32_e32 v52, v52
	v_exp_f32_e32 v53, v53
	v_add_f32_e32 v54, 1.0, v54
	v_add_f32_e32 v55, 1.0, v55
	v_add_f32_e32 v56, 1.0, v56
	v_add_f32_e32 v57, 1.0, v57
	v_add_f32_e32 v50, 1.0, v50
	v_add_f32_e32 v51, 1.0, v51
	v_add_f32_e32 v52, 1.0, v52
	v_add_f32_e32 v53, 1.0, v53
	v_rcp_f32_e32 v54, v54
	v_rcp_f32_e32 v55, v55
	v_rcp_f32_e32 v56, v56
	v_rcp_f32_e32 v57, v57
	v_rcp_f32_e32 v50, v50
	v_rcp_f32_e32 v51, v51
	v_rcp_f32_e32 v52, v52
	v_rcp_f32_e32 v53, v53
	s_waitcnt vmcnt(24)
	v_lshlrev_b32_e32 v204, 16, v160
	v_lshlrev_b32_e32 v205, 16, v164
	v_and_b32_e32 v160, 0xffff0000, v160
	v_and_b32_e32 v164, 0xffff0000, v164
	v_fma_f32 v54, v54, v204, v205
	v_fma_f32 v55, v55, v160, v164
	v_lshlrev_b32_e32 v204, 16, v161
	v_lshlrev_b32_e32 v205, 16, v165
	v_and_b32_e32 v161, 0xffff0000, v161
	v_and_b32_e32 v165, 0xffff0000, v165
	v_fma_f32 v56, v56, v204, v205
	v_fma_f32 v57, v57, v161, v165
	v_lshlrev_b32_e32 v204, 16, v162
	v_lshlrev_b32_e32 v205, 16, v166
	v_and_b32_e32 v162, 0xffff0000, v162
	v_and_b32_e32 v166, 0xffff0000, v166
	v_fma_f32 v50, v50, v204, v205
	v_fma_f32 v51, v51, v162, v166
	v_lshlrev_b32_e32 v204, 16, v163
	v_lshlrev_b32_e32 v205, 16, v167
	v_and_b32_e32 v163, 0xffff0000, v163
	v_and_b32_e32 v167, 0xffff0000, v167
	v_fma_f32 v52, v52, v204, v205
	v_fma_f32 v53, v53, v163, v167
	v_add_u32_e32 v207, 0x80000, v206
	global_store_dwordx4 v207, v[54:57], s[4:5] offset:512
	global_store_dwordx4 v207, v[50:53], s[4:5] offset:528
	v_mul_f32_e32 v46, s80, v46
	v_mul_f32_e32 v47, s80, v47
	v_mul_f32_e32 v48, s80, v48
	v_mul_f32_e32 v49, s80, v49
	v_mul_f32_e32 v42, s80, v42
	v_mul_f32_e32 v43, s80, v43
	v_mul_f32_e32 v44, s80, v44
	v_mul_f32_e32 v45, s80, v45
	v_exp_f32_e32 v46, v46
	v_exp_f32_e32 v47, v47
	v_exp_f32_e32 v48, v48
	v_exp_f32_e32 v49, v49
	v_exp_f32_e32 v42, v42
	v_exp_f32_e32 v43, v43
	v_exp_f32_e32 v44, v44
	v_exp_f32_e32 v45, v45
	v_add_f32_e32 v46, 1.0, v46
	v_add_f32_e32 v47, 1.0, v47
	v_add_f32_e32 v48, 1.0, v48
	v_add_f32_e32 v49, 1.0, v49
	v_add_f32_e32 v42, 1.0, v42
	v_add_f32_e32 v43, 1.0, v43
	v_add_f32_e32 v44, 1.0, v44
	v_add_f32_e32 v45, 1.0, v45
	v_rcp_f32_e32 v46, v46
	v_rcp_f32_e32 v47, v47
	v_rcp_f32_e32 v48, v48
	v_rcp_f32_e32 v49, v49
	v_rcp_f32_e32 v42, v42
	v_rcp_f32_e32 v43, v43
	v_rcp_f32_e32 v44, v44
	v_rcp_f32_e32 v45, v45
	s_waitcnt vmcnt(22)
	v_lshlrev_b32_e32 v204, 16, v168
	v_lshlrev_b32_e32 v205, 16, v172
	v_and_b32_e32 v168, 0xffff0000, v168
	v_and_b32_e32 v172, 0xffff0000, v172
	v_fma_f32 v46, v46, v204, v205
	v_fma_f32 v47, v47, v168, v172
	v_lshlrev_b32_e32 v204, 16, v169
	v_lshlrev_b32_e32 v205, 16, v173
	v_and_b32_e32 v169, 0xffff0000, v169
	v_and_b32_e32 v173, 0xffff0000, v173
	v_fma_f32 v48, v48, v204, v205
	v_fma_f32 v49, v49, v169, v173
	v_lshlrev_b32_e32 v204, 16, v170
	v_lshlrev_b32_e32 v205, 16, v174
	v_and_b32_e32 v170, 0xffff0000, v170
	v_and_b32_e32 v174, 0xffff0000, v174
	v_fma_f32 v42, v42, v204, v205
	v_fma_f32 v43, v43, v170, v174
	v_lshlrev_b32_e32 v204, 16, v171
	v_lshlrev_b32_e32 v205, 16, v175
	v_and_b32_e32 v171, 0xffff0000, v171
	v_and_b32_e32 v175, 0xffff0000, v175
	v_fma_f32 v44, v44, v204, v205
	v_fma_f32 v45, v45, v171, v175
	v_add_u32_e32 v207, 0x90000, v206
	global_store_dwordx4 v207, v[46:49], s[4:5]
	global_store_dwordx4 v207, v[42:45], s[4:5] offset:16
	v_mul_f32_e32 v38, s80, v38
	v_mul_f32_e32 v39, s80, v39
	v_mul_f32_e32 v40, s80, v40
	v_mul_f32_e32 v41, s80, v41
	v_mul_f32_e32 v34, s80, v34
	v_mul_f32_e32 v35, s80, v35
	v_mul_f32_e32 v36, s80, v36
	v_mul_f32_e32 v37, s80, v37
	v_exp_f32_e32 v38, v38
	v_exp_f32_e32 v39, v39
	v_exp_f32_e32 v40, v40
	v_exp_f32_e32 v41, v41
	v_exp_f32_e32 v34, v34
	v_exp_f32_e32 v35, v35
	v_exp_f32_e32 v36, v36
	v_exp_f32_e32 v37, v37
	v_add_f32_e32 v38, 1.0, v38
	v_add_f32_e32 v39, 1.0, v39
	v_add_f32_e32 v40, 1.0, v40
	v_add_f32_e32 v41, 1.0, v41
	v_add_f32_e32 v34, 1.0, v34
	v_add_f32_e32 v35, 1.0, v35
	v_add_f32_e32 v36, 1.0, v36
	v_add_f32_e32 v37, 1.0, v37
	v_rcp_f32_e32 v38, v38
	v_rcp_f32_e32 v39, v39
	v_rcp_f32_e32 v40, v40
	v_rcp_f32_e32 v41, v41
	v_rcp_f32_e32 v34, v34
	v_rcp_f32_e32 v35, v35
	v_rcp_f32_e32 v36, v36
	v_rcp_f32_e32 v37, v37
	s_waitcnt vmcnt(20)
; __device__ __forceinline__ float bflo(unsigned u) { return __uint_as_float(u << 16); }
; __device__ __forceinline__ float bfhi(unsigned u) { return __uint_as_float(u & 0xffff0000u); }
; __device__ __forceinline__ f32x2 sigm2(f32x2 v) { const f32x2 a = v * -1.4426950408889634f; f32x2 e; e.x = __builtin_amdgcn_exp2f(a.x); e.y = __builtin_amdgcn_exp2f(a.y); const f32x2 d = e + 1.0f; f32x2 r; r.x = __builtin_amdgcn_rcpf(d.x); r.y = __builtin_amdgcn_rcpf(d.y); return r; }
;     __device__ __forceinline__ void operator()(const pg8::f32x4 (&acc)[2][2][4][2], const Unit& u, int wr, int wc, int fr_, int fq_) const {
;     ...
;                 for (int bj = 0; bj < 2; ++bj) { const size_t off = (size_t)row * DM + col0 + bj * HALF;
;                     const u32x4 t = *(const u32x4*)(T + off); const u32x4 xb = *(const u32x4*)(XB + off);
;                     pg8::f32x4 x0 = {bflo(xb.x), bfhi(xb.x), bflo(xb.y), bfhi(xb.y)}, x1 = {bflo(xb.z), bfhi(xb.z), bflo(xb.w), bfhi(xb.w)};
;                     const pg8::f32x4 a0 = acc[ai][bj][m][0], a1 = acc[ai][bj][m][1];
;                     { const f32x2 s0 = sigm2((f32x2){a0[0], a0[1]}), s1 = sigm2((f32x2){a0[2], a0[3]}), s2 = sigm2((f32x2){a1[0], a1[1]}), s3 = sigm2((f32x2){a1[2], a1[3]});
;                       x0[0] += s0.x * bflo(t.x); x0[1] += s0.y * bfhi(t.x); x0[2] += s1.x * bflo(t.y); x0[3] += s1.y * bfhi(t.y);
;                       x1[0] += s2.x * bflo(t.z); x1[1] += s2.y * bfhi(t.z); x1[2] += s3.x * bflo(t.w); x1[3] += s3.y * bfhi(t.w); }
;                     if (f32out) { *(pg8::f32x4*)(Xo + off) = x0; *(pg8::f32x4*)(Xo + off + 4) = x1; }
	v_lshlrev_b32_e32 v204, 16, v176
	v_lshlrev_b32_e32 v205, 16, v180
	v_and_b32_e32 v176, 0xffff0000, v176
	v_and_b32_e32 v180, 0xffff0000, v180
	v_fma_f32 v38, v38, v204, v205
	v_fma_f32 v39, v39, v176, v180
	v_lshlrev_b32_e32 v204, 16, v177
	v_lshlrev_b32_e32 v205, 16, v181
	v_and_b32_e32 v177, 0xffff0000, v177
	v_and_b32_e32 v181, 0xffff0000, v181
	v_fma_f32 v40, v40, v204, v205
	v_fma_f32 v41, v41, v177, v181
	v_lshlrev_b32_e32 v204, 16, v178
	v_lshlrev_b32_e32 v205, 16, v182
	v_and_b32_e32 v178, 0xffff0000, v178
	v_and_b32_e32 v182, 0xffff0000, v182
	v_fma_f32 v34, v34, v204, v205
	v_fma_f32 v35, v35, v178, v182
	v_lshlrev_b32_e32 v204, 16, v179
	v_lshlrev_b32_e32 v205, 16, v183
	v_and_b32_e32 v179, 0xffff0000, v179
	v_and_b32_e32 v183, 0xffff0000, v183
	v_fma_f32 v36, v36, v204, v205
	v_fma_f32 v37, v37, v179, v183
	v_add_u32_e32 v207, 0x90000, v206
	global_store_dwordx4 v207, v[38:41], s[4:5] offset:512
	global_store_dwordx4 v207, v[34:37], s[4:5] offset:528
	v_mul_f32_e32 v30, s80, v30
	v_mul_f32_e32 v31, s80, v31
	v_mul_f32_e32 v32, s80, v32
	v_mul_f32_e32 v33, s80, v33
	v_mul_f32_e32 v26, s80, v26
	v_mul_f32_e32 v27, s80, v27
	v_mul_f32_e32 v28, s80, v28
	v_mul_f32_e32 v29, s80, v29
	v_exp_f32_e32 v30, v30
	v_exp_f32_e32 v31, v31
	v_exp_f32_e32 v32, v32
	v_exp_f32_e32 v33, v33
	v_exp_f32_e32 v26, v26
	v_exp_f32_e32 v27, v27
	v_exp_f32_e32 v28, v28
	v_exp_f32_e32 v29, v29
	v_add_f32_e32 v30, 1.0, v30
	v_add_f32_e32 v31, 1.0, v31
	v_add_f32_e32 v32, 1.0, v32
	v_add_f32_e32 v33, 1.0, v33
	v_add_f32_e32 v26, 1.0, v26
	v_add_f32_e32 v27, 1.0, v27
	v_add_f32_e32 v28, 1.0, v28
	v_add_f32_e32 v29, 1.0, v29
	v_rcp_f32_e32 v30, v30
	v_rcp_f32_e32 v31, v31
	v_rcp_f32_e32 v32, v32
	v_rcp_f32_e32 v33, v33
	v_rcp_f32_e32 v26, v26
	v_rcp_f32_e32 v27, v27
	v_rcp_f32_e32 v28, v28
	v_rcp_f32_e32 v29, v29
	s_waitcnt vmcnt(18)
	v_lshlrev_b32_e32 v204, 16, v184
	v_lshlrev_b32_e32 v205, 16, v188
	v_and_b32_e32 v184, 0xffff0000, v184
	v_and_b32_e32 v188, 0xffff0000, v188
	v_fma_f32 v30, v30, v204, v205
	v_fma_f32 v31, v31, v184, v188
	v_lshlrev_b32_e32 v204, 16, v185
	v_lshlrev_b32_e32 v205, 16, v189
	v_and_b32_e32 v185, 0xffff0000, v185
	v_and_b32_e32 v189, 0xffff0000, v189
	v_fma_f32 v32, v32, v204, v205
	v_fma_f32 v33, v33, v185, v189
	v_lshlrev_b32_e32 v204, 16, v186
	v_lshlrev_b32_e32 v205, 16, v190
	v_and_b32_e32 v186, 0xffff0000, v186
	v_and_b32_e32 v190, 0xffff0000, v190
	v_fma_f32 v26, v26, v204, v205
	v_fma_f32 v27, v27, v186, v190
	v_lshlrev_b32_e32 v204, 16, v187
	v_lshlrev_b32_e32 v205, 16, v191
	v_and_b32_e32 v187, 0xffff0000, v187
	v_and_b32_e32 v191, 0xffff0000, v191
	v_fma_f32 v28, v28, v204, v205
	v_fma_f32 v29, v29, v187, v191
	v_add_u32_e32 v207, 0xa0000, v206
	global_store_dwordx4 v207, v[30:33], s[4:5]
	global_store_dwordx4 v207, v[26:29], s[4:5] offset:16
	v_mul_f32_e32 v22, s80, v22
	v_mul_f32_e32 v23, s80, v23
	v_mul_f32_e32 v24, s80, v24
	v_mul_f32_e32 v25, s80, v25
	v_mul_f32_e32 v18, s80, v18
	v_mul_f32_e32 v19, s80, v19
	v_mul_f32_e32 v20, s80, v20
	v_mul_f32_e32 v21, s80, v21
	v_exp_f32_e32 v22, v22
	v_exp_f32_e32 v23, v23
	v_exp_f32_e32 v24, v24
	v_exp_f32_e32 v25, v25
	v_exp_f32_e32 v18, v18
	v_exp_f32_e32 v19, v19
	v_exp_f32_e32 v20, v20
	v_exp_f32_e32 v21, v21
	v_add_f32_e32 v22, 1.0, v22
	v_add_f32_e32 v23, 1.0, v23
	v_add_f32_e32 v24, 1.0, v24
	v_add_f32_e32 v25, 1.0, v25
	v_add_f32_e32 v18, 1.0, v18
	v_add_f32_e32 v19, 1.0, v19
	v_add_f32_e32 v20, 1.0, v20
	v_add_f32_e32 v21, 1.0, v21
	v_rcp_f32_e32 v22, v22
	v_rcp_f32_e32 v23, v23
	v_rcp_f32_e32 v24, v24
	v_rcp_f32_e32 v25, v25
	v_rcp_f32_e32 v18, v18
	v_rcp_f32_e32 v19, v19
	v_rcp_f32_e32 v20, v20
	v_rcp_f32_e32 v21, v21
	s_waitcnt vmcnt(16)
; #define PG8_BAR __builtin_amdgcn_s_barrier()
; __device__ __forceinline__ unsigned pk2(float lo, float hi) { return pg8::cvt_pk_bf16(lo, hi); }
; __device__ __forceinline__ float bflo(unsigned u) { return __uint_as_float(u << 16); }
; __device__ __forceinline__ float bfhi(unsigned u) { return __uint_as_float(u & 0xffff0000u); }
; template <class Epi, class Sched, bool ALIGN_EPI = false, bool SP2 = false>
; __device__ __forceinline__ void gemm_phase(PG8_LAS unsigned char* lds, const Gemm g, const Sched& S, const Epi& E) {
;     ...
;         if (!has_next) break;
; #pragma unroll
;         for (int a = 0; a < 2; ++a)
; #pragma unroll
;             for (int b = 0; b < 2; ++b)
; #pragma unroll
;                 for (int m = 0; m < 4; ++m)
; #pragma unroll
;                     for (int n = 0; n < 2; ++n) acc[a][b][m][n] = (f32x4){0.f, 0.f, 0.f, 0.f};
;         cur = nxt; cA = nA; cB = nB; ++ui;
;         if constexpr (ALIGN_EPI) { if (wr == 1) PG8_BAR; }
;     }
;     __device__ __forceinline__ void operator()(const pg8::f32x4 (&acc)[2][2][4][2], const Unit& u, int wr, int wc, int fr_, int fq_) const {
;     ...
;                 for (int bj = 0; bj < 2; ++bj) { const size_t off = (size_t)row * DM + col0 + bj * HALF;
;                     const u32x4 t = *(const u32x4*)(T + off); const u32x4 xb = *(const u32x4*)(XB + off);
;                     pg8::f32x4 x0 = {bflo(xb.x), bfhi(xb.x), bflo(xb.y), bfhi(xb.y)}, x1 = {bflo(xb.z), bfhi(xb.z), bflo(xb.w), bfhi(xb.w)};
;                     const pg8::f32x4 a0 = acc[ai][bj][m][0], a1 = acc[ai][bj][m][1];
;                     { const f32x2 s0 = sigm2((f32x2){a0[0], a0[1]}), s1 = sigm2((f32x2){a0[2], a0[3]}), s2 = sigm2((f32x2){a1[0], a1[1]}), s3 = sigm2((f32x2){a1[2], a1[3]});
;                       x0[0] += s0.x * bflo(t.x); x0[1] += s0.y * bfhi(t.x); x0[2] += s1.x * bflo(t.y); x0[3] += s1.y * bfhi(t.y);
;                       x1[0] += s2.x * bflo(t.z); x1[1] += s2.y * bfhi(t.z); x1[2] += s3.x * bflo(t.w); x1[3] += s3.y * bfhi(t.w); }
;                     if (f32out) { *(pg8::f32x4*)(Xo + off) = x0; *(pg8::f32x4*)(Xo + off + 4) = x1; }
;                     else { u32x4 w; w.x = pk2(x0[0], x0[1]); w.y = pk2(x0[2], x0[3]); w.z = pk2(x1[0], x1[1]); w.w = pk2(x1[2], x1[3]); *(u32x4*)((bf16_t*)Xo + off) = w; } } }
	v_lshlrev_b32_e32 v204, 16, v192
	v_lshlrev_b32_e32 v205, 16, v196
	v_and_b32_e32 v192, 0xffff0000, v192
	v_and_b32_e32 v196, 0xffff0000, v196
	v_fma_f32 v22, v22, v204, v205
	v_fma_f32 v23, v23, v192, v196
	v_lshlrev_b32_e32 v204, 16, v193
	v_lshlrev_b32_e32 v205, 16, v197
	v_and_b32_e32 v193, 0xffff0000, v193
	v_and_b32_e32 v197, 0xffff0000, v197
	v_fma_f32 v24, v24, v204, v205
	v_fma_f32 v25, v25, v193, v197
	v_lshlrev_b32_e32 v204, 16, v194
	v_lshlrev_b32_e32 v205, 16, v198
	v_and_b32_e32 v194, 0xffff0000, v194
	v_and_b32_e32 v198, 0xffff0000, v198
	v_fma_f32 v18, v18, v204, v205
	v_fma_f32 v19, v19, v194, v198
	v_lshlrev_b32_e32 v204, 16, v195
	v_lshlrev_b32_e32 v205, 16, v199
	v_and_b32_e32 v195, 0xffff0000, v195
	v_and_b32_e32 v199, 0xffff0000, v199
	v_fma_f32 v20, v20, v204, v205
	v_fma_f32 v21, v21, v195, v199
	v_add_u32_e32 v207, 0xa0000, v206
	global_store_dwordx4 v207, v[22:25], s[4:5] offset:512
	global_store_dwordx4 v207, v[18:21], s[4:5] offset:528
	v_mul_f32_e32 v14, s80, v14
	v_mul_f32_e32 v15, s80, v15
	v_mul_f32_e32 v16, s80, v16
	v_mul_f32_e32 v17, s80, v17
	v_mul_f32_e32 v10, s80, v10
	v_mul_f32_e32 v11, s80, v11
	v_mul_f32_e32 v12, s80, v12
	v_mul_f32_e32 v13, s80, v13
	v_exp_f32_e32 v14, v14
	v_exp_f32_e32 v15, v15
	v_exp_f32_e32 v16, v16
	v_exp_f32_e32 v17, v17
	v_exp_f32_e32 v10, v10
	v_exp_f32_e32 v11, v11
	v_exp_f32_e32 v12, v12
	v_exp_f32_e32 v13, v13
	v_add_f32_e32 v14, 1.0, v14
	v_add_f32_e32 v15, 1.0, v15
	v_add_f32_e32 v16, 1.0, v16
	v_add_f32_e32 v17, 1.0, v17
	v_add_f32_e32 v10, 1.0, v10
	v_add_f32_e32 v11, 1.0, v11
	v_add_f32_e32 v12, 1.0, v12
	v_add_f32_e32 v13, 1.0, v13
	v_rcp_f32_e32 v14, v14
	v_rcp_f32_e32 v15, v15
	v_rcp_f32_e32 v16, v16
	v_rcp_f32_e32 v17, v17
	v_rcp_f32_e32 v10, v10
	v_rcp_f32_e32 v11, v11
	v_rcp_f32_e32 v12, v12
	v_rcp_f32_e32 v13, v13
	s_waitcnt vmcnt(14)
	v_lshlrev_b32_e32 v204, 16, v140
	v_lshlrev_b32_e32 v205, 16, v144
	v_and_b32_e32 v140, 0xffff0000, v140
	v_and_b32_e32 v144, 0xffff0000, v144
	v_fma_f32 v14, v14, v204, v205
	v_fma_f32 v15, v15, v140, v144
	v_lshlrev_b32_e32 v204, 16, v141
	v_lshlrev_b32_e32 v205, 16, v145
	v_and_b32_e32 v141, 0xffff0000, v141
	v_and_b32_e32 v145, 0xffff0000, v145
	v_fma_f32 v16, v16, v204, v205
	v_fma_f32 v17, v17, v141, v145
	v_lshlrev_b32_e32 v204, 16, v142
	v_lshlrev_b32_e32 v205, 16, v146
	v_and_b32_e32 v142, 0xffff0000, v142
	v_and_b32_e32 v146, 0xffff0000, v146
	v_fma_f32 v10, v10, v204, v205
	v_fma_f32 v11, v11, v142, v146
	v_lshlrev_b32_e32 v204, 16, v143
	v_lshlrev_b32_e32 v205, 16, v147
	v_and_b32_e32 v143, 0xffff0000, v143
	v_and_b32_e32 v147, 0xffff0000, v147
	v_fma_f32 v12, v12, v204, v205
	v_fma_f32 v13, v13, v143, v147
	v_add_u32_e32 v207, 0xb0000, v206
	global_store_dwordx4 v207, v[14:17], s[4:5]
	global_store_dwordx4 v207, v[10:13], s[4:5] offset:16
	v_mul_f32_e32 v6, s80, v6
	v_mul_f32_e32 v7, s80, v7
	v_mul_f32_e32 v8, s80, v8
	v_mul_f32_e32 v9, s80, v9
	v_mul_f32_e32 v2, s80, v2
	v_mul_f32_e32 v3, s80, v3
	v_mul_f32_e32 v4, s80, v4
	v_mul_f32_e32 v5, s80, v5
	v_exp_f32_e32 v6, v6
	v_exp_f32_e32 v7, v7
	v_exp_f32_e32 v8, v8
	v_exp_f32_e32 v9, v9
	v_exp_f32_e32 v2, v2
	v_exp_f32_e32 v3, v3
	v_exp_f32_e32 v4, v4
	v_exp_f32_e32 v5, v5
	v_add_f32_e32 v6, 1.0, v6
	v_add_f32_e32 v7, 1.0, v7
	v_add_f32_e32 v8, 1.0, v8
	v_add_f32_e32 v9, 1.0, v9
	v_add_f32_e32 v2, 1.0, v2
	v_add_f32_e32 v3, 1.0, v3
	v_add_f32_e32 v4, 1.0, v4
	v_add_f32_e32 v5, 1.0, v5
	v_rcp_f32_e32 v6, v6
	v_rcp_f32_e32 v7, v7
	v_rcp_f32_e32 v8, v8
	v_rcp_f32_e32 v9, v9
	v_rcp_f32_e32 v2, v2
	v_rcp_f32_e32 v3, v3
	v_rcp_f32_e32 v4, v4
	v_rcp_f32_e32 v5, v5
	s_waitcnt vmcnt(12)
	v_lshlrev_b32_e32 v204, 16, v152
	v_lshlrev_b32_e32 v205, 16, v156
	v_and_b32_e32 v152, 0xffff0000, v152
	v_and_b32_e32 v156, 0xffff0000, v156
	v_fma_f32 v6, v6, v204, v205
	v_fma_f32 v7, v7, v152, v156
	v_lshlrev_b32_e32 v204, 16, v153
	v_lshlrev_b32_e32 v205, 16, v157
	v_and_b32_e32 v153, 0xffff0000, v153
	v_and_b32_e32 v157, 0xffff0000, v157
	v_fma_f32 v8, v8, v204, v205
	v_fma_f32 v9, v9, v153, v157
	v_lshlrev_b32_e32 v204, 16, v154
	v_lshlrev_b32_e32 v205, 16, v158
	v_and_b32_e32 v154, 0xffff0000, v154
	v_and_b32_e32 v158, 0xffff0000, v158
	v_fma_f32 v2, v2, v204, v205
	v_fma_f32 v3, v3, v154, v158
	v_lshlrev_b32_e32 v204, 16, v155
	v_lshlrev_b32_e32 v205, 16, v159
	v_and_b32_e32 v155, 0xffff0000, v155
	v_and_b32_e32 v159, 0xffff0000, v159
	v_fma_f32 v4, v4, v204, v205
	v_fma_f32 v5, v5, v155, v159
	v_add_u32_e32 v207, 0xb0000, v206
	global_store_dwordx4 v207, v[6:9], s[4:5] offset:512
	global_store_dwordx4 v207, v[2:5], s[4:5] offset:528
.Lg3epi_done:
.LBB0_1792:
	s_or_b64 exec, exec, s[28:29]
	s_andn2_b64 vcc, exec, s[2:3]
	s_mov_b64 s[2:3], -1
	s_cbranch_vccnz .LBB0_1709
	s_andn2_b64 vcc, exec, s[12:13]
	s_cbranch_vccnz .LBB0_1708
	s_barrier
	s_branch .LBB0_1708
